# v11: sample-row small GEMM tiles load their operands coalesced (LDS-DMA / 128B-per-row register loads) and transpose through LDS into MFMA fragments instead of per-lane fragment loads from global (up,
# speedup vs baseline: 1.0736x; 1.0301x over previous
; template <int NT, int ACT, int K>
; __device__ __forceinline__ void small_gemm_tile(LAS unsigned char* lds, const bf16* __restrict__ A, const bf16* __restrict__ Bt, bf16* __restrict__ O, int ldc, int lda, int ldb, const float* __restrict__ rs, int m0, int n0, int tid) {
;     ...
;     const int wave = __builtin_amdgcn_readfirstlane(tid >> 6), lane = tid & 63, fr = lane & 15, fq = lane >> 4;
;     const bf16* ap = A + (size_t)(m0 + fr) * lda + wave * KW + fq * 8;
;     const bf16* bp = Bt + (size_t)(n0 + fr) * ldb + wave * KW + fq * 8;
;     f32x4 acc[4][NT];
; #pragma unroll
;     for (int m = 0; m < 4; ++m)
; #pragma unroll
;         for (int n = 0; n < NT; ++n) acc[m][n] = (f32x4){0.f, 0.f, 0.f, 0.f};
;     if constexpr (NCH == 1) {
;         bf16x8 fa[4][4], fb[4][NT];
; #pragma unroll
;         for (int s_ = 0; s_ < 4; ++s_) {
; #pragma unroll
;             for (int m = 0; m < 4; ++m) fa[s_][m] = *(const bf16x8*)(ap + (size_t)m * 16 * lda + s_ * 32);
; #pragma unroll
;             for (int n = 0; n < NT; ++n) fb[s_][n] = *(const bf16x8*)(bp + (size_t)n * 16 * ldb + s_ * 32); }
; __global__ void __launch_bounds__(NWAVES * 64, 2) hybrid_fwd(Args args) {
;     ...
;                 for (int j = bx; j < (MS / 64) * (FF / 64); j += G) small_gemm_tile<4, 1, DM>(lds, (const bf16*)args.out, (const bf16*)(wl + W_UP), (bf16*)(ws + WS_H), FP, 2 * DM, DM + WPAD, (const float*)(ws + WS_RS), MP + (j & 7) * 64, SMALL_TN(j, FF / 64) * 64, tid);
.Lws_nc_up:
	s_waitcnt vmcnt(3)
	v_ashrrev_i32_e32 v1, 31, v186
	v_lshrrev_b32_e32 v1, 29, v1
	v_add_u32_e32 v1, v186, v1
	s_waitcnt vmcnt(0)
	v_bfe_u32 v0, v186, 4, 2
	v_ashrrev_i32_e32 v13, 3, v1
	v_bfe_i32 v1, v186, 28, 1
	v_lshlrev_b32_e32 v2, 3, v0
	v_lshlrev_b32_e32 v14, 10, v0
	v_lshlrev_b32_e32 v0, 3, v186
	v_lshrrev_b32_e32 v1, 26, v1
	v_add_u32_e32 v1, v0, v1
	v_and_b32_e32 v1, 0xffffffc0, v1
	v_lshlrev_b32_e32 v3, 2, v153
	v_lshl_add_u32 v4, v186, 5, 0
	v_sub_u32_e32 v0, v0, v1
	v_add_u32_e32 v5, 0x10000, v4
	v_add_u32_e32 v6, 0x10010, v4
	v_add_u32_e32 v7, 0x14000, v4
	v_add_u32_e32 v8, 0x14010, v4
	v_add_u32_e32 v9, 0x18000, v4
	v_add_u32_e32 v10, 0x18010, v4
	v_add_u32_e32 v11, 0x1c000, v4
	v_add_u32_e32 v12, 0x1c010, v4
	v_ashrrev_i32_e32 v1, 31, v0
	v_add3_u32 v14, 0, v3, v14
	s_waitcnt lgkmcnt(0)
	s_lshl_b32 s2, s3, 6
	v_lshlrev_b32_e32 v2, 1, v2
	v_readlane_b32 s6, v253, 51
	s_mov_b32 s7, s60
	v_and_b32_e32 v230, 63, v186
	v_lshrrev_b32_e32 v231, 3, v230
	v_and_b32_e32 v232, 7, v230
	v_lshrrev_b32_e32 v233, 1, v231
	v_xor_b32_e32 v232, v232, v233
	v_lshlrev_b32_e32 v232, 4, v232
	v_lshl_or_b32 v212, v231, 12, v232
	v_lshl_or_b32 v220, v231, 11, v232
	v_xor_b32_e32 v213, 64, v212
	v_add_u32_e32 v213, 0x8000, v213
	v_xor_b32_e32 v221, 64, v220
	v_add_u32_e32 v221, 0x4000, v221
	v_add_u32_e32 v214, 0x10000, v212
	v_add_u32_e32 v222, 0x8000, v220
	v_add_u32_e32 v215, 0x10000, v213
	v_add_u32_e32 v223, 0x8000, v221
	v_add_u32_e32 v216, 0x20000, v212
	v_add_u32_e32 v224, 0x10000, v220
	v_add_u32_e32 v217, 0x20000, v213
	v_add_u32_e32 v225, 0x10000, v221
	v_add_u32_e32 v218, 0x30000, v212
	v_add_u32_e32 v226, 0x18000, v220
	v_add_u32_e32 v219, 0x30000, v213
	v_add_u32_e32 v227, 0x18000, v221
	v_and_b32_e32 v231, 15, v230
	v_lshrrev_b32_e32 v232, 4, v230
	v_lshrrev_b32_e32 v233, 1, v231
	v_xor_b32_e32 v232, v232, v233
	v_lshlrev_b32_e32 v232, 4, v232
	v_lshl_or_b32 v228, v231, 7, v232
	v_lshrrev_b32_e32 v233, 6, v186
	v_lshl_add_u32 v228, v233, 14, v228
	v_xor_b32_e32 v229, 64, v228
.LBB0_60:
	s_and_b32 s5, s6, 0x1c0
	v_readfirstlane_b32 s8, v186
	s_bitset1_b32 s5, 14
	s_ashr_i32 s10, s8, 6
	s_lshl_b32 s8, s10, 7
	s_ashr_i32 s9, s8, 31
	s_lshl_b64 s[8:9], s[8:9], 1
	s_lshl_b32 s4, s7, 3
	s_andn2_b32 s4, s4, 63
	s_lshl_b32 s100, s5, 12
	s_add_u32 s100, s100, s18
	s_addc_u32 s101, s19, 0
	s_add_u32 s100, s100, s8
	s_addc_u32 s101, s101, s9
	s_add_u32 s8, s8, s0
	s_addc_u32 s9, s9, s1
	s_lshl_b32 vcc_lo, s4, 11
	s_add_u32 s8, s8, vcc_lo
	s_addc_u32 s9, s9, 0
	s_lshl_b32 m0, s10, 14
	s_nop 0
	global_load_lds_dwordx4 v212, s[100:101]
	s_add_i32 m0, m0, 0x400
	s_nop 0
	global_load_lds_dwordx4 v213, s[100:101]
	s_add_i32 m0, m0, 0x400
	s_nop 0
	global_load_lds_dwordx4 v214, s[100:101]
	s_add_i32 m0, m0, 0x400
	s_nop 0
	global_load_lds_dwordx4 v215, s[100:101]
	s_add_i32 m0, m0, 0x400
	s_nop 0
	global_load_lds_dwordx4 v216, s[100:101]
	s_add_i32 m0, m0, 0x400
	s_nop 0
	global_load_lds_dwordx4 v217, s[100:101]
	s_add_i32 m0, m0, 0x400
	s_nop 0
	global_load_lds_dwordx4 v218, s[100:101]
	s_add_i32 m0, m0, 0x400
	s_nop 0
	global_load_lds_dwordx4 v219, s[100:101]
	s_add_i32 m0, m0, 0x400
	s_nop 0
	global_load_lds_dwordx4 v220, s[8:9]
	s_add_i32 m0, m0, 0x400
	s_nop 0
	global_load_lds_dwordx4 v221, s[8:9]
	s_add_i32 m0, m0, 0x400
	s_nop 0
	global_load_lds_dwordx4 v222, s[8:9]
	s_add_i32 m0, m0, 0x400
	s_nop 0
	global_load_lds_dwordx4 v223, s[8:9]
	s_add_i32 m0, m0, 0x400
	s_nop 0
	global_load_lds_dwordx4 v224, s[8:9]
	s_add_i32 m0, m0, 0x400
	s_nop 0
	global_load_lds_dwordx4 v225, s[8:9]
	s_add_i32 m0, m0, 0x400
	s_nop 0
	global_load_lds_dwordx4 v226, s[8:9]
	s_add_i32 m0, m0, 0x400
	s_nop 0
	global_load_lds_dwordx4 v227, s[8:9]
	s_waitcnt vmcnt(0)
	ds_read_b128 v[16:19], v228 offset:0
	ds_read_b128 v[20:23], v229 offset:0
	ds_read_b128 v[24:27], v228 offset:2048
	ds_read_b128 v[28:31], v229 offset:2048
	ds_read_b128 v[32:35], v228 offset:4096
	ds_read_b128 v[36:39], v229 offset:4096
	ds_read_b128 v[40:43], v228 offset:6144
	ds_read_b128 v[44:47], v229 offset:6144
	ds_read_b128 v[48:51], v228 offset:8192
	ds_read_b128 v[52:55], v229 offset:8192
	ds_read_b128 v[56:59], v228 offset:10240
	ds_read_b128 v[60:63], v229 offset:10240
	ds_read_b128 v[64:67], v228 offset:12288
	ds_read_b128 v[68:71], v229 offset:12288
	ds_read_b128 v[72:75], v228 offset:14336
	ds_read_b128 v[76:79], v229 offset:14336
	s_waitcnt lgkmcnt(0)
; template <int NT, int ACT, int K>
; __device__ __forceinline__ void small_gemm_tile(LAS unsigned char* lds, const bf16* __restrict__ A, const bf16* __restrict__ Bt, bf16* __restrict__ O, int ldc, int lda, int ldb, const float* __restrict__ rs, int m0, int n0, int tid) {
;     ...
;     if constexpr (NCH == 1) {
;         bf16x8 fa[4][4], fb[4][NT];
; #pragma unroll
;         for (int s_ = 0; s_ < 4; ++s_) {
; #pragma unroll
;             for (int m = 0; m < 4; ++m) fa[s_][m] = *(const bf16x8*)(ap + (size_t)m * 16 * lda + s_ * 32);
; #pragma unroll
;             for (int n = 0; n < NT; ++n) fb[s_][n] = *(const bf16x8*)(bp + (size_t)n * 16 * ldb + s_ * 32); }
;         __builtin_amdgcn_sched_barrier(0);
; #pragma unroll
;         for (int s_ = 0; s_ < 4; ++s_)
; #pragma unroll
;             for (int m = 0; m < 4; ++m)
; #pragma unroll
;                 for (int n = 0; n < NT; ++n) acc[m][n] = __builtin_amdgcn_mfma_f32_16x16x32_bf16(fa[s_][m], fb[s_][n], acc[m][n], 0, 0, 0);
;         __builtin_amdgcn_sched_barrier(0);
	s_add_u32 s100, s100, 0x80
	s_addc_u32 s101, s101, 0
	s_add_u32 s8, s8, 0x80
	s_addc_u32 s9, s9, 0
	s_lshl_b32 m0, s10, 14
	s_nop 0
	global_load_lds_dwordx4 v212, s[100:101]
	s_add_i32 m0, m0, 0x400
	s_nop 0
	global_load_lds_dwordx4 v213, s[100:101]
	s_add_i32 m0, m0, 0x400
	s_nop 0
	global_load_lds_dwordx4 v214, s[100:101]
	s_add_i32 m0, m0, 0x400
	s_nop 0
	global_load_lds_dwordx4 v215, s[100:101]
	s_add_i32 m0, m0, 0x400
	s_nop 0
	global_load_lds_dwordx4 v216, s[100:101]
	s_add_i32 m0, m0, 0x400
	s_nop 0
	global_load_lds_dwordx4 v217, s[100:101]
	s_add_i32 m0, m0, 0x400
	s_nop 0
	global_load_lds_dwordx4 v218, s[100:101]
	s_add_i32 m0, m0, 0x400
	s_nop 0
	global_load_lds_dwordx4 v219, s[100:101]
	s_add_i32 m0, m0, 0x400
	s_nop 0
	global_load_lds_dwordx4 v220, s[8:9]
	s_add_i32 m0, m0, 0x400
	s_nop 0
	global_load_lds_dwordx4 v221, s[8:9]
	s_add_i32 m0, m0, 0x400
	s_nop 0
	global_load_lds_dwordx4 v222, s[8:9]
	s_add_i32 m0, m0, 0x400
	s_nop 0
	global_load_lds_dwordx4 v223, s[8:9]
	s_add_i32 m0, m0, 0x400
	s_nop 0
	global_load_lds_dwordx4 v224, s[8:9]
	s_add_i32 m0, m0, 0x400
	s_nop 0
	global_load_lds_dwordx4 v225, s[8:9]
	s_add_i32 m0, m0, 0x400
	s_nop 0
	global_load_lds_dwordx4 v226, s[8:9]
	s_add_i32 m0, m0, 0x400
	s_nop 0
	global_load_lds_dwordx4 v227, s[8:9]
	v_mfma_f32_16x16x32_bf16 v[154:157], v[16:19], v[48:51], 0
	v_mfma_f32_16x16x32_bf16 v[158:161], v[16:19], v[56:59], 0
	v_mfma_f32_16x16x32_bf16 v[162:165], v[16:19], v[64:67], 0
	v_mfma_f32_16x16x32_bf16 v[16:19], v[16:19], v[72:75], 0
	v_mfma_f32_16x16x32_bf16 v[188:191], v[24:27], v[48:51], 0
	v_mfma_f32_16x16x32_bf16 v[192:195], v[24:27], v[56:59], 0
	v_mfma_f32_16x16x32_bf16 v[196:199], v[24:27], v[64:67], 0
	v_mfma_f32_16x16x32_bf16 v[24:27], v[24:27], v[72:75], 0
	v_mfma_f32_16x16x32_bf16 v[200:203], v[32:35], v[48:51], 0
	v_mfma_f32_16x16x32_bf16 v[204:207], v[32:35], v[56:59], 0
	v_mfma_f32_16x16x32_bf16 v[208:211], v[32:35], v[64:67], 0
	v_mfma_f32_16x16x32_bf16 v[32:35], v[32:35], v[72:75], 0
	v_mfma_f32_16x16x32_bf16 v[48:51], v[40:43], v[48:51], 0
	v_mfma_f32_16x16x32_bf16 v[56:59], v[40:43], v[56:59], 0
	v_mfma_f32_16x16x32_bf16 v[64:67], v[40:43], v[64:67], 0
	v_mfma_f32_16x16x32_bf16 v[40:43], v[40:43], v[72:75], 0
	v_mfma_f32_16x16x32_bf16 v[72:75], v[20:23], v[52:55], v[154:157]
	v_mfma_f32_16x16x32_bf16 v[154:157], v[20:23], v[60:63], v[158:161]
	v_mfma_f32_16x16x32_bf16 v[158:161], v[20:23], v[68:71], v[162:165]
	v_mfma_f32_16x16x32_bf16 v[16:19], v[20:23], v[76:79], v[16:19]
	v_mfma_f32_16x16x32_bf16 v[20:23], v[28:31], v[52:55], v[188:191]
	v_mfma_f32_16x16x32_bf16 v[162:165], v[28:31], v[60:63], v[192:195]
	v_mfma_f32_16x16x32_bf16 v[188:191], v[28:31], v[68:71], v[196:199]
	v_mfma_f32_16x16x32_bf16 v[24:27], v[28:31], v[76:79], v[24:27]
	v_mfma_f32_16x16x32_bf16 v[28:31], v[36:39], v[52:55], v[200:203]
	v_mfma_f32_16x16x32_bf16 v[192:195], v[36:39], v[60:63], v[204:207]
	v_mfma_f32_16x16x32_bf16 v[196:199], v[36:39], v[68:71], v[208:211]
	v_mfma_f32_16x16x32_bf16 v[32:35], v[36:39], v[76:79], v[32:35]
	v_mfma_f32_16x16x32_bf16 v[36:39], v[44:47], v[52:55], v[48:51]
	v_mfma_f32_16x16x32_bf16 v[48:51], v[44:47], v[60:63], v[56:59]
	v_mfma_f32_16x16x32_bf16 v[52:55], v[44:47], v[68:71], v[64:67]
	v_mfma_f32_16x16x32_bf16 v[40:43], v[44:47], v[76:79], v[40:43]
	s_waitcnt vmcnt(0)
	ds_read_b128 v[80:83], v228 offset:0
	ds_read_b128 v[84:87], v229 offset:0
	ds_read_b128 v[88:91], v228 offset:2048
	ds_read_b128 v[92:95], v229 offset:2048
	ds_read_b128 v[96:99], v228 offset:4096
	ds_read_b128 v[100:103], v229 offset:4096
	ds_read_b128 v[104:107], v228 offset:6144
	ds_read_b128 v[108:111], v229 offset:6144
	ds_read_b128 v[112:115], v228 offset:8192
	ds_read_b128 v[116:119], v229 offset:8192
	ds_read_b128 v[120:123], v228 offset:10240
	ds_read_b128 v[124:127], v229 offset:10240
	ds_read_b128 v[136:139], v228 offset:12288
	ds_read_b128 v[140:143], v229 offset:12288
	ds_read_b128 v[144:147], v228 offset:14336
	ds_read_b128 v[148:151], v229 offset:14336
	s_waitcnt lgkmcnt(0)
	v_mfma_f32_16x16x32_bf16 v[44:47], v[80:83], v[112:115], v[72:75]
	v_mfma_f32_16x16x32_bf16 v[56:59], v[80:83], v[120:123], v[154:157]
	v_mfma_f32_16x16x32_bf16 v[60:63], v[80:83], v[136:139], v[158:161]
	v_mfma_f32_16x16x32_bf16 v[16:19], v[80:83], v[144:147], v[16:19]
	v_mfma_f32_16x16x32_bf16 v[20:23], v[88:91], v[112:115], v[20:23]
	v_mfma_f32_16x16x32_bf16 v[64:67], v[88:91], v[120:123], v[162:165]
	v_mfma_f32_16x16x32_bf16 v[68:71], v[88:91], v[136:139], v[188:191]
	v_mfma_f32_16x16x32_bf16 v[24:27], v[88:91], v[144:147], v[24:27]
	v_mfma_f32_16x16x32_bf16 v[28:31], v[96:99], v[112:115], v[28:31]
	v_mfma_f32_16x16x32_bf16 v[72:75], v[96:99], v[120:123], v[192:195]
	v_mfma_f32_16x16x32_bf16 v[76:79], v[96:99], v[136:139], v[196:199]
	v_mfma_f32_16x16x32_bf16 v[32:35], v[96:99], v[144:147], v[32:35]
	v_mfma_f32_16x16x32_bf16 v[36:39], v[104:107], v[112:115], v[36:39]
	v_mfma_f32_16x16x32_bf16 v[48:51], v[104:107], v[120:123], v[48:51]
	v_mfma_f32_16x16x32_bf16 v[52:55], v[104:107], v[136:139], v[52:55]
	v_mfma_f32_16x16x32_bf16 v[40:43], v[104:107], v[144:147], v[40:43]
	v_mfma_f32_16x16x32_bf16 v[44:47], v[84:87], v[116:119], v[44:47]
	v_mfma_f32_16x16x32_bf16 v[56:59], v[84:87], v[124:127], v[56:59]
	v_mfma_f32_16x16x32_bf16 v[60:63], v[84:87], v[140:143], v[60:63]
	v_mfma_f32_16x16x32_bf16 v[16:19], v[84:87], v[148:151], v[16:19]
	v_mfma_f32_16x16x32_bf16 v[20:23], v[92:95], v[116:119], v[20:23]
	v_mfma_f32_16x16x32_bf16 v[64:67], v[92:95], v[124:127], v[64:67]
	v_mfma_f32_16x16x32_bf16 v[68:71], v[92:95], v[140:143], v[68:71]
	v_mfma_f32_16x16x32_bf16 v[24:27], v[92:95], v[148:151], v[24:27]
; #define LAS __attribute__((address_space(3)))
; __device__ __forceinline__ unsigned pk2(float lo, float hi) { return f2bf(lo) | (f2bf(hi) << 16); }
; template <int NT, int ACT, int K>
; __device__ __forceinline__ void small_gemm_tile(LAS unsigned char* lds, const bf16* __restrict__ A, const bf16* __restrict__ Bt, bf16* __restrict__ O, int ldc, int lda, int ldb, const float* __restrict__ rs, int m0, int n0, int tid) {
;     ...
;     LAS float* P = (LAS float*)lds + wave * (64 * NC);
; #pragma unroll
;     for (int m = 0; m < 4; ++m)
; #pragma unroll
;         for (int n = 0; n < NT; ++n)
; #pragma unroll
;             for (int i = 0; i < 4; ++i) P[(m * 16 + fq * 4 + i) * NC + n * 16 + fr] = acc[m][n][i];
;     __syncthreads();
;     constexpr int EPT = 64 * NC / 512;
;     const int e0 = tid * EPT, row = e0 / NC, col = e0 % NC;
;     float r[EPT];
; #pragma unroll
;     for (int j = 0; j < EPT; ++j) r[j] = 0.f;
; #pragma unroll
;     for (int w = 0; w < 8; ++w) { const LAS f32x4* q = (const LAS f32x4*)((LAS float*)lds + w * (64 * NC) + e0);
; #pragma unroll
;         for (int j = 0; j < EPT / 4; ++j) { const f32x4 v = q[j]; r[4 * j] += v[0]; r[4 * j + 1] += v[1]; r[4 * j + 2] += v[2]; r[4 * j + 3] += v[3]; } }
;     if (rs) { const float sc = rs[m0 + row];
; #pragma unroll
;         for (int j = 0; j < EPT; ++j) r[j] *= sc; }
;     if (ACT == 1) {
; #pragma unroll
;         for (int j = 0; j < EPT; ++j) { const float t = fmaxf(r[j], 0.f); r[j] = t * t; } }
;     bf16* op = O + (size_t)(m0 + row) * ldc + n0 + col;
;     if (EPT == 8) { v4u w; w.x = pk2(r[0], r[1]); w.y = pk2(r[2], r[3]); w.z = pk2(r[4 % EPT], r[5 % EPT]); w.w = pk2(r[6 % EPT], r[7 % EPT]); *(v4u*)op = w; }
;     else { v2u w; w.x = pk2(r[0], r[1]); w.y = pk2(r[2], r[3]); *(v2u*)op = w; }
;     __syncthreads();
; }
	v_mfma_f32_16x16x32_bf16 v[28:31], v[100:103], v[116:119], v[28:31]
	v_mfma_f32_16x16x32_bf16 v[72:75], v[100:103], v[124:127], v[72:75]
	v_mfma_f32_16x16x32_bf16 v[76:79], v[100:103], v[140:143], v[76:79]
	v_mfma_f32_16x16x32_bf16 v[32:35], v[100:103], v[148:151], v[32:35]
	v_mfma_f32_16x16x32_bf16 v[36:39], v[108:111], v[116:119], v[36:39]
	v_mfma_f32_16x16x32_bf16 v[48:51], v[108:111], v[124:127], v[48:51]
	v_mfma_f32_16x16x32_bf16 v[52:55], v[108:111], v[140:143], v[52:55]
	v_mfma_f32_16x16x32_bf16 v[40:43], v[108:111], v[148:151], v[40:43]
	v_lshl_add_u32 v3, s10, 14, v14
	v_add_u32_e32 v15, 0x1000, v3
	ds_write2_b32 v3, v44, v56 offset1:16
	ds_write2_b32 v3, v45, v57 offset0:64 offset1:80
	ds_write2_b32 v3, v46, v58 offset0:128 offset1:144
	ds_write2_b32 v3, v47, v59 offset0:192 offset1:208
	ds_write2_b32 v3, v60, v16 offset0:32 offset1:48
	ds_write2_b32 v3, v61, v17 offset0:96 offset1:112
	ds_write2_b32 v3, v62, v18 offset0:160 offset1:176
	ds_write2_b32 v3, v63, v19 offset0:224 offset1:240
	ds_write2_b32 v15, v20, v64 offset1:16
	ds_write2_b32 v15, v21, v65 offset0:64 offset1:80
	ds_write2_b32 v15, v22, v66 offset0:128 offset1:144
	ds_write2_b32 v15, v23, v67 offset0:192 offset1:208
	ds_write2_b32 v15, v68, v24 offset0:32 offset1:48
	ds_write2_b32 v15, v69, v25 offset0:96 offset1:112
	ds_write2_b32 v15, v70, v26 offset0:160 offset1:176
	ds_write2_b32 v15, v71, v27 offset0:224 offset1:240
	v_add_u32_e32 v24, s5, v13
	v_ashrrev_i32_e32 v25, 31, v24
	v_add_u32_e32 v15, 0x2000, v3
	v_add_u32_e32 v3, 0x3000, v3
	v_lshl_add_u64 v[20:21], v[24:25], 2, s[82:83]
	ds_write2_b32 v15, v28, v72 offset1:16
	ds_write2_b32 v15, v29, v73 offset0:64 offset1:80
	ds_write2_b32 v15, v30, v74 offset0:128 offset1:144
	ds_write2_b32 v15, v31, v75 offset0:192 offset1:208
	ds_write2_b32 v15, v76, v32 offset0:32 offset1:48
	ds_write2_b32 v15, v77, v33 offset0:96 offset1:112
	ds_write2_b32 v15, v78, v34 offset0:160 offset1:176
	ds_write2_b32 v15, v79, v35 offset0:224 offset1:240
	ds_write2_b32 v3, v36, v48 offset1:16
	ds_write2_b32 v3, v37, v49 offset0:64 offset1:80
	ds_write2_b32 v3, v38, v50 offset0:128 offset1:144
	ds_write2_b32 v3, v39, v51 offset0:192 offset1:208
	ds_write2_b32 v3, v52, v40 offset0:32 offset1:48
	ds_write2_b32 v3, v53, v41 offset0:96 offset1:112
	ds_write2_b32 v3, v54, v42 offset0:160 offset1:176
	ds_write2_b32 v3, v55, v43 offset0:224 offset1:240
	s_waitcnt lgkmcnt(0)
	s_barrier
	global_load_dword v3, v[20:21], off
	ds_read_b128 v[16:19], v4
	ds_read_b128 v[20:23], v4 offset:16
	s_movk_i32 s5, 0x2080
	s_add_i32 s7, s7, s3
	s_add_i32 s6, s6, s2
	s_waitcnt lgkmcnt(1)
	v_add_f32_e32 v15, 0, v16
	v_add_f32_e32 v25, 0, v17
	v_add_f32_e32 v26, 0, v18
	v_add_f32_e32 v27, 0, v19
	s_waitcnt lgkmcnt(0)
	v_add_f32_e32 v28, 0, v20
	ds_read_b128 v[16:19], v4 offset:16384
	v_add_f32_e32 v29, 0, v21
	v_add_f32_e32 v30, 0, v22
	v_add_f32_e32 v31, 0, v23
	ds_read_b128 v[20:23], v4 offset:16400
	s_waitcnt lgkmcnt(1)
	v_add_f32_e32 v15, v15, v16
	v_add_f32_e32 v25, v25, v17
	v_add_f32_e32 v26, v26, v18
	v_add_f32_e32 v27, v27, v19
	s_waitcnt lgkmcnt(0)
	v_add_f32_e32 v28, v28, v20
	ds_read_b128 v[16:19], v4 offset:32768
	v_add_f32_e32 v29, v29, v21
	v_add_f32_e32 v30, v30, v22
	v_add_f32_e32 v31, v31, v23
	ds_read_b128 v[20:23], v4 offset:32784
	s_waitcnt lgkmcnt(1)
	v_add_f32_e32 v15, v15, v16
	v_add_f32_e32 v25, v25, v17
	v_add_f32_e32 v26, v26, v18
	v_add_f32_e32 v27, v27, v19
	s_waitcnt lgkmcnt(0)
	v_add_f32_e32 v28, v28, v20
	ds_read_b128 v[16:19], v4 offset:49152
	v_add_f32_e32 v29, v29, v21
	v_add_f32_e32 v30, v30, v22
	v_add_f32_e32 v31, v31, v23
	ds_read_b128 v[20:23], v4 offset:49168
	s_waitcnt lgkmcnt(1)
	v_add_f32_e32 v15, v15, v16
	v_add_f32_e32 v25, v25, v17
	v_add_f32_e32 v26, v26, v18
	v_add_f32_e32 v27, v27, v19
	s_waitcnt lgkmcnt(0)
	v_add_f32_e32 v28, v28, v20
	ds_read_b128 v[16:19], v5
	v_add_f32_e32 v29, v29, v21
	v_add_f32_e32 v30, v30, v22
	v_add_f32_e32 v31, v31, v23
	ds_read_b128 v[20:23], v6
	s_waitcnt lgkmcnt(1)
	v_add_f32_e32 v15, v15, v16
	v_add_f32_e32 v25, v25, v17
	v_add_f32_e32 v26, v26, v18
	v_add_f32_e32 v27, v27, v19
	s_waitcnt lgkmcnt(0)
	v_add_f32_e32 v28, v28, v20
	ds_read_b128 v[16:19], v7
	v_add_f32_e32 v29, v29, v21
	v_add_f32_e32 v30, v30, v22
	v_add_f32_e32 v31, v31, v23
	ds_read_b128 v[20:23], v8
	s_waitcnt lgkmcnt(1)
	v_add_f32_e32 v15, v15, v16
	v_add_f32_e32 v25, v25, v17
	v_add_f32_e32 v26, v26, v18
	v_add_f32_e32 v27, v27, v19
	s_waitcnt lgkmcnt(0)
	v_add_f32_e32 v28, v28, v20
	ds_read_b128 v[16:19], v9
	v_add_f32_e32 v29, v29, v21
	v_add_f32_e32 v30, v30, v22
	v_add_f32_e32 v31, v31, v23
	ds_read_b128 v[20:23], v10
	s_waitcnt lgkmcnt(1)
	v_add_f32_e32 v15, v15, v16
	v_add_f32_e32 v25, v25, v17
	v_add_f32_e32 v26, v26, v18
	v_add_f32_e32 v27, v27, v19
	s_waitcnt lgkmcnt(0)
	v_add_f32_e32 v28, v28, v20
	ds_read_b128 v[16:19], v11
	v_add_f32_e32 v29, v29, v21
	v_add_f32_e32 v30, v30, v22
	v_add_f32_e32 v31, v31, v23
	ds_read_b128 v[20:23], v12
	s_waitcnt lgkmcnt(1)
	v_add_f32_e32 v15, v15, v16
	v_add_f32_e32 v16, v25, v17
	v_add_f32_e32 v17, v26, v18
	v_add_f32_e32 v18, v27, v19
	s_waitcnt lgkmcnt(0)
	v_add_f32_e32 v19, v28, v20
	v_add_f32_e32 v20, v29, v21
	v_add_f32_e32 v21, v30, v22
	v_add_f32_e32 v22, v31, v23
	s_waitcnt vmcnt(0)
	v_mul_f32_e32 v15, v3, v15
	v_mul_f32_e32 v23, v3, v16
	v_mul_f32_e32 v17, v3, v17
	v_mul_f32_e32 v25, v3, v18
	v_mul_f32_e32 v26, v3, v19
	v_mul_f32_e32 v27, v3, v20
	v_mul_f32_e32 v21, v3, v21
	v_mul_f32_e32 v3, v3, v22
	v_max_f32_e32 v18, 0, v23
	v_max_f32_e32 v19, 0, v25
	v_max_f32_e32 v22, 0, v27
	v_max_f32_e32 v23, 0, v3
	v_max_f32_e32 v16, 0, v15
	v_max_f32_e32 v17, 0, v17
	v_max_f32_e32 v20, 0, v26
	v_max_f32_e32 v21, 0, v21
	v_mov_b64_e32 v[26:27], s[64:65]
	v_pk_mul_f32 v[18:19], v[18:19], v[18:19]
	v_pk_mul_f32 v[22:23], v[22:23], v[22:23]
	v_mad_i64_i32 v[24:25], s[8:9], v24, s5, v[26:27]
	v_pk_mul_f32 v[16:17], v[16:17], v[16:17]
	v_pk_mul_f32 v[20:21], v[20:21], v[20:21]
	v_bfe_u32 v3, v23, 16, 1
	v_bfe_u32 v15, v22, 16, 1
	v_bfe_u32 v26, v19, 16, 1
	v_bfe_u32 v27, v18, 16, 1
	v_add3_u32 v27, v18, v27, s90
	v_add3_u32 v26, v19, v26, s90
	v_add3_u32 v15, v22, v15, s90
	v_add3_u32 v3, v23, v3, s90
	v_bfe_u32 v18, v16, 16, 1
	v_bfe_u32 v19, v17, 16, 1
	v_bfe_u32 v22, v20, 16, 1
	v_bfe_u32 v23, v21, 16, 1
	s_ashr_i32 s5, s4, 31
	v_add3_u32 v21, v21, v23, s90
	v_add3_u32 v20, v20, v22, s90
	v_add3_u32 v17, v17, v19, s90
	v_add3_u32 v16, v16, v18, s90
	v_lshl_add_u64 v[24:25], s[4:5], 1, v[24:25]
	v_lshrrev_b32_e32 v16, 16, v16
	v_lshrrev_b32_e32 v17, 16, v17
	v_lshrrev_b32_e32 v18, 16, v20
	v_lshrrev_b32_e32 v19, 16, v21
	v_lshl_add_u64 v[24:25], v[0:1], 1, v[24:25]
	v_and_or_b32 v19, v3, s91, v19
	v_and_or_b32 v18, v15, s91, v18
	v_and_or_b32 v17, v26, s91, v17
	v_and_or_b32 v16, v27, s91, v16
	s_cmpk_gt_i32 s7, 0x1ff
	global_store_dwordx4 v[24:25], v[16:19], off
	s_barrier
	s_cbranch_scc0 .LBB0_60

; template <int NT, int ACT, int K>
; __device__ __forceinline__ void small_gemm_tile(LAS unsigned char* lds, const bf16* __restrict__ A, const bf16* __restrict__ Bt, bf16* __restrict__ O, int ldc, int lda, int ldb, const float* __restrict__ rs, int m0, int n0, int tid) {
;     ...
;     const int wave = __builtin_amdgcn_readfirstlane(tid >> 6), lane = tid & 63, fr = lane & 15, fq = lane >> 4;
;     const bf16* ap = A + (size_t)(m0 + fr) * lda + wave * KW + fq * 8;
;     const bf16* bp = Bt + (size_t)(n0 + fr) * ldb + wave * KW + fq * 8;
;     f32x4 acc[4][NT];
; #pragma unroll
;     for (int m = 0; m < 4; ++m)
; #pragma unroll
;         for (int n = 0; n < NT; ++n) acc[m][n] = (f32x4){0.f, 0.f, 0.f, 0.f};
;     if constexpr (NCH == 1) {
;         bf16x8 fa[4][4], fb[4][NT];
; #pragma unroll
;         for (int s_ = 0; s_ < 4; ++s_) {
; #pragma unroll
;             for (int m = 0; m < 4; ++m) fa[s_][m] = *(const bf16x8*)(ap + (size_t)m * 16 * lda + s_ * 32);
; #pragma unroll
;             for (int n = 0; n < NT; ++n) fb[s_][n] = *(const bf16x8*)(bp + (size_t)n * 16 * ldb + s_ * 32); }
; __global__ void __launch_bounds__(NWAVES * 64, 2) hybrid_fwd(Args args) {
;     ...
;                 if (k == 0) { for (int j = bx; j < (MS / 64) * (INW / 64); j += G) small_gemm_tile<4, 0, DM>(lds, A, Bt, (bf16*)(ws + WS_H + SGRP_BASE + (size_t)(j & 7) * SGRP_BYTES) - (size_t)(MP + (j & 7) * 64) * ZP, ZP, 2 * DM, DM + WPAD, (const float*)(ws + WS_RS), MP + (j & 7) * 64, SMALL_TN(j, INW / 64) * 64, tid); }
.Lws_nc_pl:
	v_readlane_b32 s6, v253, 30
	v_readlane_b32 s7, v253, 31
	s_waitcnt vmcnt(2)
	v_lshl_add_u32 v4, v153, 2, 0
	s_mov_b64 s[8:9], -1
	s_waitcnt vmcnt(0)
	v_cndmask_b32_e64 v0, 0, 1, s[6:7]
	s_andn2_b64 vcc, exec, s[58:59]
	v_cmp_ne_u32_e64 s[6:7], 1, v0
	s_mov_b64 s[64:65], s[52:53]
	s_mov_b32 s37, 0x18000
	s_mov_b32 s57, 0x8000
	s_mov_b32 s58, 0x20000
	s_mov_b32 s59, 0x30000
	s_mov_b32 s68, s54
	s_mov_b32 s69, s55
	v_readlane_b32 s70, v254, 58
	s_cbranch_vccnz .LBB0_498
	v_readlane_b32 s40, v253, 57
	s_and_b64 vcc, exec, s[6:7]
	v_readlane_b32 s54, v254, 7
	v_readlane_b32 s55, v254, 8
	v_readlane_b32 s41, v253, 58
	v_readlane_b32 s42, v253, 59
	v_readlane_b32 s43, v253, 60
	v_readlane_b32 s44, v253, 61
	v_readlane_b32 s45, v253, 62
	v_readlane_b32 s46, v253, 63
	v_readlane_b32 s47, v254, 0
	v_readlane_b32 s48, v254, 1
	v_readlane_b32 s49, v254, 2
	v_readlane_b32 s50, v254, 3
	v_readlane_b32 s51, v254, 4
	v_readlane_b32 s52, v254, 5
	v_readlane_b32 s53, v254, 6
	s_cbranch_vccnz .LBB0_497
	v_ashrrev_i32_e32 v1, 31, v186
	v_lshrrev_b32_e32 v1, 29, v1
	v_add_u32_e32 v1, v186, v1
	s_waitcnt vmcnt(0)
	v_ashrrev_i32_e32 v14, 3, v1
	v_bfe_i32 v1, v186, 28, 1
	v_lshlrev_b32_e32 v0, 3, v186
	v_lshrrev_b32_e32 v1, 26, v1
	v_add_u32_e32 v1, v0, v1
	v_bfe_u32 v3, v186, 4, 2
	v_and_b32_e32 v1, 0xffffffc0, v1
	v_lshlrev_b32_e32 v2, 3, v3
	v_lshl_add_u32 v5, v186, 5, 0
	v_sub_u32_e32 v0, v0, v1
	v_add_u32_e32 v6, 0x10000, v5
	v_add_u32_e32 v7, 0x10010, v5
	v_add_u32_e32 v8, 0x14000, v5
	v_add_u32_e32 v9, 0x14010, v5
	v_add_u32_e32 v10, 0x18000, v5
	v_add_u32_e32 v11, 0x18010, v5
	v_add_u32_e32 v12, 0x1c000, v5
	v_add_u32_e32 v13, 0x1c010, v5
	v_ashrrev_i32_e32 v1, 31, v0
	v_lshl_add_u32 v15, v3, 10, v4
	v_lshlrev_b32_e32 v2, 1, v2
	s_mov_b32 s2, s60
	v_and_b32_e32 v230, 63, v186
	v_lshrrev_b32_e32 v231, 3, v230
	v_and_b32_e32 v232, 7, v230
	v_lshrrev_b32_e32 v233, 1, v231
	v_xor_b32_e32 v232, v232, v233
	v_lshlrev_b32_e32 v232, 4, v232
	v_lshl_or_b32 v212, v231, 12, v232
	v_lshl_or_b32 v220, v231, 11, v232
	v_xor_b32_e32 v213, 64, v212
	v_add_u32_e32 v213, 0x8000, v213
	v_xor_b32_e32 v221, 64, v220
	v_add_u32_e32 v221, 0x4000, v221
	v_add_u32_e32 v214, 0x10000, v212
	v_add_u32_e32 v222, 0x8000, v220
	v_add_u32_e32 v215, 0x10000, v213
	v_add_u32_e32 v223, 0x8000, v221
	v_add_u32_e32 v216, 0x20000, v212
	v_add_u32_e32 v224, 0x10000, v220
	v_add_u32_e32 v217, 0x20000, v213
	v_add_u32_e32 v225, 0x10000, v221
	v_add_u32_e32 v218, 0x30000, v212
	v_add_u32_e32 v226, 0x18000, v220
	v_add_u32_e32 v219, 0x30000, v213
	v_add_u32_e32 v227, 0x18000, v221
	v_and_b32_e32 v231, 15, v230
	v_lshrrev_b32_e32 v232, 4, v230
	v_lshrrev_b32_e32 v233, 1, v231
	v_xor_b32_e32 v232, v232, v233
	v_lshlrev_b32_e32 v232, 4, v232
	v_lshl_or_b32 v228, v231, 7, v232
	v_lshrrev_b32_e32 v233, 6, v186
	v_lshl_add_u32 v228, v233, 14, v228
	v_xor_b32_e32 v229, 64, v228
.LBB0_496:
	s_and_b32 s8, s2, 7
	s_mul_i32 s9, s8, 0x82000
	s_add_u32 s9, s62, s9
	s_addc_u32 s14, s63, 0
	s_lshl_b32 s15, s8, 6
	s_bitset1_b32 s15, 14
	s_mul_i32 s8, s15, 0x1080
	s_sub_u32 s8, s9, s8
	v_readfirstlane_b32 s16, v186
	s_subb_u32 s9, s14, 0
	s_ashr_i32 s18, s16, 6
	s_lshl_b32 s16, s18, 7
	s_ashr_i32 s17, s16, 31
	s_lshl_b64 s[16:17], s[16:17], 1
	s_lshl_b32 s14, s2, 3
	s_andn2_b32 s14, s14, 63
	s_lshl_b32 s100, s15, 12
	s_add_u32 s100, s100, s54
	s_addc_u32 s101, s55, 0
	s_add_u32 s100, s100, s16
	s_addc_u32 s101, s101, s17
	s_add_u32 s16, s16, s10
	s_addc_u32 s17, s17, s11
	s_lshl_b32 vcc_lo, s14, 11
	s_add_u32 s16, s16, vcc_lo
	s_addc_u32 s17, s17, 0
	s_lshl_b32 m0, s18, 14
	s_nop 0
	global_load_lds_dwordx4 v212, s[100:101]
	s_add_i32 m0, m0, 0x400
	s_nop 0
	global_load_lds_dwordx4 v213, s[100:101]
	s_add_i32 m0, m0, 0x400
	s_nop 0
	global_load_lds_dwordx4 v214, s[100:101]
	s_add_i32 m0, m0, 0x400
	s_nop 0
	global_load_lds_dwordx4 v215, s[100:101]
	s_add_i32 m0, m0, 0x400
	s_nop 0
	global_load_lds_dwordx4 v216, s[100:101]
	s_add_i32 m0, m0, 0x400
	s_nop 0
	global_load_lds_dwordx4 v217, s[100:101]
	s_add_i32 m0, m0, 0x400
	s_nop 0
	global_load_lds_dwordx4 v218, s[100:101]
	s_add_i32 m0, m0, 0x400
	s_nop 0
	global_load_lds_dwordx4 v219, s[100:101]
	s_add_i32 m0, m0, 0x400
	s_nop 0
	global_load_lds_dwordx4 v220, s[16:17]
	s_add_i32 m0, m0, 0x400
	s_nop 0
	global_load_lds_dwordx4 v221, s[16:17]
	s_add_i32 m0, m0, 0x400
	s_nop 0
	global_load_lds_dwordx4 v222, s[16:17]
	s_add_i32 m0, m0, 0x400
	s_nop 0
	global_load_lds_dwordx4 v223, s[16:17]
	s_add_i32 m0, m0, 0x400
	s_nop 0
	global_load_lds_dwordx4 v224, s[16:17]
	s_add_i32 m0, m0, 0x400
	s_nop 0
	global_load_lds_dwordx4 v225, s[16:17]
	s_add_i32 m0, m0, 0x400
	s_nop 0
	global_load_lds_dwordx4 v226, s[16:17]
	s_add_i32 m0, m0, 0x400
	s_nop 0
	global_load_lds_dwordx4 v227, s[16:17]
	s_waitcnt vmcnt(0)
	ds_read_b128 v[16:19], v228 offset:0
	ds_read_b128 v[20:23], v229 offset:0
	ds_read_b128 v[24:27], v228 offset:2048
	ds_read_b128 v[28:31], v229 offset:2048
	ds_read_b128 v[32:35], v228 offset:4096
	ds_read_b128 v[36:39], v229 offset:4096
	ds_read_b128 v[40:43], v228 offset:6144
	ds_read_b128 v[44:47], v229 offset:6144
	ds_read_b128 v[48:51], v228 offset:8192
	ds_read_b128 v[52:55], v229 offset:8192
	ds_read_b128 v[56:59], v228 offset:10240
	ds_read_b128 v[60:63], v229 offset:10240
	ds_read_b128 v[64:67], v228 offset:12288
	ds_read_b128 v[68:71], v229 offset:12288
	ds_read_b128 v[72:75], v228 offset:14336
	ds_read_b128 v[76:79], v229 offset:14336
	s_waitcnt lgkmcnt(0)
; template <int NT, int ACT, int K>
; __device__ __forceinline__ void small_gemm_tile(LAS unsigned char* lds, const bf16* __restrict__ A, const bf16* __restrict__ Bt, bf16* __restrict__ O, int ldc, int lda, int ldb, const float* __restrict__ rs, int m0, int n0, int tid) {
;     ...
;     if constexpr (NCH == 1) {
;         bf16x8 fa[4][4], fb[4][NT];
; #pragma unroll
;         for (int s_ = 0; s_ < 4; ++s_) {
; #pragma unroll
;             for (int m = 0; m < 4; ++m) fa[s_][m] = *(const bf16x8*)(ap + (size_t)m * 16 * lda + s_ * 32);
; #pragma unroll
;             for (int n = 0; n < NT; ++n) fb[s_][n] = *(const bf16x8*)(bp + (size_t)n * 16 * ldb + s_ * 32); }
;         __builtin_amdgcn_sched_barrier(0);
; #pragma unroll
;         for (int s_ = 0; s_ < 4; ++s_)
; #pragma unroll
;             for (int m = 0; m < 4; ++m)
; #pragma unroll
;                 for (int n = 0; n < NT; ++n) acc[m][n] = __builtin_amdgcn_mfma_f32_16x16x32_bf16(fa[s_][m], fb[s_][n], acc[m][n], 0, 0, 0);
;         __builtin_amdgcn_sched_barrier(0);
	s_add_u32 s100, s100, 0x80
	s_addc_u32 s101, s101, 0
	s_add_u32 s16, s16, 0x80
	s_addc_u32 s17, s17, 0
	s_lshl_b32 m0, s18, 14
	s_nop 0
	global_load_lds_dwordx4 v212, s[100:101]
	s_add_i32 m0, m0, 0x400
	s_nop 0
	global_load_lds_dwordx4 v213, s[100:101]
	s_add_i32 m0, m0, 0x400
	s_nop 0
	global_load_lds_dwordx4 v214, s[100:101]
	s_add_i32 m0, m0, 0x400
	s_nop 0
	global_load_lds_dwordx4 v215, s[100:101]
	s_add_i32 m0, m0, 0x400
	s_nop 0
	global_load_lds_dwordx4 v216, s[100:101]
	s_add_i32 m0, m0, 0x400
	s_nop 0
	global_load_lds_dwordx4 v217, s[100:101]
	s_add_i32 m0, m0, 0x400
	s_nop 0
	global_load_lds_dwordx4 v218, s[100:101]
	s_add_i32 m0, m0, 0x400
	s_nop 0
	global_load_lds_dwordx4 v219, s[100:101]
	s_add_i32 m0, m0, 0x400
	s_nop 0
	global_load_lds_dwordx4 v220, s[16:17]
	s_add_i32 m0, m0, 0x400
	s_nop 0
	global_load_lds_dwordx4 v221, s[16:17]
	s_add_i32 m0, m0, 0x400
	s_nop 0
	global_load_lds_dwordx4 v222, s[16:17]
	s_add_i32 m0, m0, 0x400
	s_nop 0
	global_load_lds_dwordx4 v223, s[16:17]
	s_add_i32 m0, m0, 0x400
	s_nop 0
	global_load_lds_dwordx4 v224, s[16:17]
	s_add_i32 m0, m0, 0x400
	s_nop 0
	global_load_lds_dwordx4 v225, s[16:17]
	s_add_i32 m0, m0, 0x400
	s_nop 0
	global_load_lds_dwordx4 v226, s[16:17]
	s_add_i32 m0, m0, 0x400
	s_nop 0
	global_load_lds_dwordx4 v227, s[16:17]
	v_mfma_f32_16x16x32_bf16 v[154:157], v[16:19], v[48:51], 0
	v_mfma_f32_16x16x32_bf16 v[158:161], v[16:19], v[56:59], 0
	v_mfma_f32_16x16x32_bf16 v[162:165], v[16:19], v[64:67], 0
	v_mfma_f32_16x16x32_bf16 v[16:19], v[16:19], v[72:75], 0
	v_mfma_f32_16x16x32_bf16 v[188:191], v[24:27], v[48:51], 0
	v_mfma_f32_16x16x32_bf16 v[192:195], v[24:27], v[56:59], 0
	v_mfma_f32_16x16x32_bf16 v[196:199], v[24:27], v[64:67], 0
	v_mfma_f32_16x16x32_bf16 v[24:27], v[24:27], v[72:75], 0
	v_mfma_f32_16x16x32_bf16 v[200:203], v[32:35], v[48:51], 0
	v_mfma_f32_16x16x32_bf16 v[204:207], v[32:35], v[56:59], 0
	v_mfma_f32_16x16x32_bf16 v[208:211], v[32:35], v[64:67], 0
	v_mfma_f32_16x16x32_bf16 v[32:35], v[32:35], v[72:75], 0
	v_mfma_f32_16x16x32_bf16 v[48:51], v[40:43], v[48:51], 0
	v_mfma_f32_16x16x32_bf16 v[56:59], v[40:43], v[56:59], 0
	v_mfma_f32_16x16x32_bf16 v[64:67], v[40:43], v[64:67], 0
	v_mfma_f32_16x16x32_bf16 v[40:43], v[40:43], v[72:75], 0
	v_mfma_f32_16x16x32_bf16 v[72:75], v[20:23], v[52:55], v[154:157]
	v_mfma_f32_16x16x32_bf16 v[154:157], v[20:23], v[60:63], v[158:161]
	v_mfma_f32_16x16x32_bf16 v[158:161], v[20:23], v[68:71], v[162:165]
	v_mfma_f32_16x16x32_bf16 v[16:19], v[20:23], v[76:79], v[16:19]
	v_mfma_f32_16x16x32_bf16 v[20:23], v[28:31], v[52:55], v[188:191]
	v_mfma_f32_16x16x32_bf16 v[162:165], v[28:31], v[60:63], v[192:195]
	v_mfma_f32_16x16x32_bf16 v[188:191], v[28:31], v[68:71], v[196:199]
	v_mfma_f32_16x16x32_bf16 v[24:27], v[28:31], v[76:79], v[24:27]
	v_mfma_f32_16x16x32_bf16 v[28:31], v[36:39], v[52:55], v[200:203]
	v_mfma_f32_16x16x32_bf16 v[192:195], v[36:39], v[60:63], v[204:207]
	v_mfma_f32_16x16x32_bf16 v[196:199], v[36:39], v[68:71], v[208:211]
	v_mfma_f32_16x16x32_bf16 v[32:35], v[36:39], v[76:79], v[32:35]
	v_mfma_f32_16x16x32_bf16 v[36:39], v[44:47], v[52:55], v[48:51]
	v_mfma_f32_16x16x32_bf16 v[48:51], v[44:47], v[60:63], v[56:59]
	v_mfma_f32_16x16x32_bf16 v[52:55], v[44:47], v[68:71], v[64:67]
	v_mfma_f32_16x16x32_bf16 v[40:43], v[44:47], v[76:79], v[40:43]
	s_waitcnt vmcnt(0)
	ds_read_b128 v[80:83], v228 offset:0
	ds_read_b128 v[84:87], v229 offset:0
	ds_read_b128 v[88:91], v228 offset:2048
	ds_read_b128 v[92:95], v229 offset:2048
	ds_read_b128 v[96:99], v228 offset:4096
	ds_read_b128 v[100:103], v229 offset:4096
	ds_read_b128 v[104:107], v228 offset:6144
	ds_read_b128 v[108:111], v229 offset:6144
	ds_read_b128 v[112:115], v228 offset:8192
	ds_read_b128 v[116:119], v229 offset:8192
	ds_read_b128 v[120:123], v228 offset:10240
	ds_read_b128 v[124:127], v229 offset:10240
	ds_read_b128 v[136:139], v228 offset:12288
	ds_read_b128 v[140:143], v229 offset:12288
	ds_read_b128 v[144:147], v228 offset:14336
	ds_read_b128 v[148:151], v229 offset:14336
	s_waitcnt lgkmcnt(0)
	v_mfma_f32_16x16x32_bf16 v[44:47], v[80:83], v[112:115], v[72:75]
	v_mfma_f32_16x16x32_bf16 v[56:59], v[80:83], v[120:123], v[154:157]
	v_mfma_f32_16x16x32_bf16 v[60:63], v[80:83], v[136:139], v[158:161]
	v_mfma_f32_16x16x32_bf16 v[16:19], v[80:83], v[144:147], v[16:19]
	v_mfma_f32_16x16x32_bf16 v[20:23], v[88:91], v[112:115], v[20:23]
	v_mfma_f32_16x16x32_bf16 v[64:67], v[88:91], v[120:123], v[162:165]
	v_mfma_f32_16x16x32_bf16 v[68:71], v[88:91], v[136:139], v[188:191]
	v_mfma_f32_16x16x32_bf16 v[24:27], v[88:91], v[144:147], v[24:27]
	v_mfma_f32_16x16x32_bf16 v[28:31], v[96:99], v[112:115], v[28:31]
	v_mfma_f32_16x16x32_bf16 v[72:75], v[96:99], v[120:123], v[192:195]
	v_mfma_f32_16x16x32_bf16 v[76:79], v[96:99], v[136:139], v[196:199]
	v_mfma_f32_16x16x32_bf16 v[32:35], v[96:99], v[144:147], v[32:35]
	v_mfma_f32_16x16x32_bf16 v[36:39], v[104:107], v[112:115], v[36:39]
	v_mfma_f32_16x16x32_bf16 v[48:51], v[104:107], v[120:123], v[48:51]
	v_mfma_f32_16x16x32_bf16 v[52:55], v[104:107], v[136:139], v[52:55]
	v_mfma_f32_16x16x32_bf16 v[40:43], v[104:107], v[144:147], v[40:43]
	v_mfma_f32_16x16x32_bf16 v[44:47], v[84:87], v[116:119], v[44:47]
	v_mfma_f32_16x16x32_bf16 v[56:59], v[84:87], v[124:127], v[56:59]
	v_mfma_f32_16x16x32_bf16 v[60:63], v[84:87], v[140:143], v[60:63]
	v_mfma_f32_16x16x32_bf16 v[16:19], v[84:87], v[148:151], v[16:19]
	v_mfma_f32_16x16x32_bf16 v[20:23], v[92:95], v[116:119], v[20:23]
	v_mfma_f32_16x16x32_bf16 v[64:67], v[92:95], v[124:127], v[64:67]
	v_mfma_f32_16x16x32_bf16 v[68:71], v[92:95], v[140:143], v[68:71]
	v_mfma_f32_16x16x32_bf16 v[24:27], v[92:95], v[148:151], v[24:27]
; #define LAS __attribute__((address_space(3)))
; template <int NT, int ACT, int K>
; __device__ __forceinline__ void small_gemm_tile(LAS unsigned char* lds, const bf16* __restrict__ A, const bf16* __restrict__ Bt, bf16* __restrict__ O, int ldc, int lda, int ldb, const float* __restrict__ rs, int m0, int n0, int tid) {
;     ...
;     LAS float* P = (LAS float*)lds + wave * (64 * NC);
; #pragma unroll
;     for (int m = 0; m < 4; ++m)
; #pragma unroll
;         for (int n = 0; n < NT; ++n)
; #pragma unroll
;             for (int i = 0; i < 4; ++i) P[(m * 16 + fq * 4 + i) * NC + n * 16 + fr] = acc[m][n][i];
;     __syncthreads();
	v_mfma_f32_16x16x32_bf16 v[28:31], v[100:103], v[116:119], v[28:31]
	v_mfma_f32_16x16x32_bf16 v[72:75], v[100:103], v[124:127], v[72:75]
	v_mfma_f32_16x16x32_bf16 v[76:79], v[100:103], v[140:143], v[76:79]
	v_mfma_f32_16x16x32_bf16 v[32:35], v[100:103], v[148:151], v[32:35]
	v_mfma_f32_16x16x32_bf16 v[36:39], v[108:111], v[116:119], v[36:39]
	v_mfma_f32_16x16x32_bf16 v[48:51], v[108:111], v[124:127], v[48:51]
	v_mfma_f32_16x16x32_bf16 v[52:55], v[108:111], v[140:143], v[52:55]
	v_mfma_f32_16x16x32_bf16 v[40:43], v[108:111], v[148:151], v[40:43]
	v_lshl_add_u32 v3, s18, 14, v15
	ds_write2_b32 v3, v44, v56 offset1:16
	ds_write2_b32 v3, v45, v57 offset0:64 offset1:80
	ds_write2_b32 v3, v46, v58 offset0:128 offset1:144
	ds_write2_b32 v3, v47, v59 offset0:192 offset1:208
	ds_write2_b32 v3, v60, v16 offset0:32 offset1:48
	ds_write2_b32 v3, v61, v17 offset0:96 offset1:112
	ds_write2_b32 v3, v62, v18 offset0:160 offset1:176
	ds_write2_b32 v3, v63, v19 offset0:224 offset1:240
	v_add_u32_e32 v16, 0x1000, v3
	v_add_u32_e32 v56, s15, v14
	ds_write2_b32 v16, v20, v64 offset1:16
	ds_write2_b32 v16, v21, v65 offset0:64 offset1:80
	ds_write2_b32 v16, v22, v66 offset0:128 offset1:144
	ds_write2_b32 v16, v23, v67 offset0:192 offset1:208
	ds_write2_b32 v16, v68, v24 offset0:32 offset1:48
	ds_write2_b32 v16, v69, v25 offset0:96 offset1:112
	ds_write2_b32 v16, v70, v26 offset0:160 offset1:176
	ds_write2_b32 v16, v71, v27 offset0:224 offset1:240
	v_add_u32_e32 v16, 0x2000, v3
	v_ashrrev_i32_e32 v57, 31, v56
	ds_write2_b32 v16, v28, v72 offset1:16
	ds_write2_b32 v16, v29, v73 offset0:64 offset1:80
	ds_write2_b32 v16, v30, v74 offset0:128 offset1:144
	ds_write2_b32 v16, v31, v75 offset0:192 offset1:208
	ds_write2_b32 v16, v76, v32 offset0:32 offset1:48
	ds_write2_b32 v16, v77, v33 offset0:96 offset1:112
	ds_write2_b32 v16, v78, v34 offset0:160 offset1:176
	ds_write2_b32 v16, v79, v35 offset0:224 offset1:240
	v_add_u32_e32 v3, 0x3000, v3
	v_lshl_add_u64 v[16:17], v[56:57], 2, s[82:83]
	ds_write2_b32 v3, v36, v48 offset1:16
	ds_write2_b32 v3, v37, v49 offset0:64 offset1:80
	ds_write2_b32 v3, v38, v50 offset0:128 offset1:144
	ds_write2_b32 v3, v39, v51 offset0:192 offset1:208
	ds_write2_b32 v3, v52, v40 offset0:32 offset1:48
	ds_write2_b32 v3, v53, v41 offset0:96 offset1:112
	ds_write2_b32 v3, v54, v42 offset0:160 offset1:176
	ds_write2_b32 v3, v55, v43 offset0:224 offset1:240
	s_waitcnt lgkmcnt(0)
	s_barrier
; #define LAS __attribute__((address_space(3)))
; __device__ __forceinline__ unsigned pk2(float lo, float hi) { return f2bf(lo) | (f2bf(hi) << 16); }
; template <int NT, int ACT, int K>
; __device__ __forceinline__ void small_gemm_tile(LAS unsigned char* lds, const bf16* __restrict__ A, const bf16* __restrict__ Bt, bf16* __restrict__ O, int ldc, int lda, int ldb, const float* __restrict__ rs, int m0, int n0, int tid) {
;     ...
;     constexpr int EPT = 64 * NC / 512;
;     const int e0 = tid * EPT, row = e0 / NC, col = e0 % NC;
;     float r[EPT];
; #pragma unroll
;     for (int j = 0; j < EPT; ++j) r[j] = 0.f;
; #pragma unroll
;     for (int w = 0; w < 8; ++w) { const LAS f32x4* q = (const LAS f32x4*)((LAS float*)lds + w * (64 * NC) + e0);
; #pragma unroll
;         for (int j = 0; j < EPT / 4; ++j) { const f32x4 v = q[j]; r[4 * j] += v[0]; r[4 * j + 1] += v[1]; r[4 * j + 2] += v[2]; r[4 * j + 3] += v[3]; } }
;     if (rs) { const float sc = rs[m0 + row];
; #pragma unroll
;         for (int j = 0; j < EPT; ++j) r[j] *= sc; }
;     if (ACT == 1) {
; #pragma unroll
;         for (int j = 0; j < EPT; ++j) { const float t = fmaxf(r[j], 0.f); r[j] = t * t; } }
;     bf16* op = O + (size_t)(m0 + row) * ldc + n0 + col;
;     if (EPT == 8) { v4u w; w.x = pk2(r[0], r[1]); w.y = pk2(r[2], r[3]); w.z = pk2(r[4 % EPT], r[5 % EPT]); w.w = pk2(r[6 % EPT], r[7 % EPT]); *(v4u*)op = w; }
;     else { v2u w; w.x = pk2(r[0], r[1]); w.y = pk2(r[2], r[3]); *(v2u*)op = w; }
;     __syncthreads();
; }
	global_load_dword v58, v[16:17], off
	ds_read_b128 v[16:19], v5
	ds_read_b128 v[20:23], v5 offset:16
	ds_read_b128 v[24:27], v5 offset:16384
	ds_read_b128 v[28:31], v5 offset:16400
	ds_read_b128 v[32:35], v5 offset:32768
	s_waitcnt lgkmcnt(4)
	v_mov_b32_e32 v36, v16
	v_mov_b32_e32 v37, v18
	v_pk_add_f32 v[36:37], v[36:37], 0 op_sel_hi:[1,0]
	s_waitcnt lgkmcnt(2)
	v_mov_b32_e32 v38, v24
	v_mov_b32_e32 v39, v26
	v_pk_add_f32 v[40:41], v[36:37], v[38:39]
	ds_read_b128 v[36:39], v5 offset:32784
	v_mov_b32_e32 v18, v17
	v_pk_add_f32 v[16:17], v[18:19], 0 op_sel_hi:[1,0]
	v_mov_b32_e32 v26, v25
	s_waitcnt lgkmcnt(1)
	v_mov_b32_e32 v43, v34
	v_pk_add_f32 v[16:17], v[16:17], v[26:27]
	v_mov_b32_e32 v34, v33
	v_pk_add_f32 v[62:63], v[16:17], v[34:35]
	v_mov_b32_e32 v16, v20
	v_mov_b32_e32 v17, v22
	v_pk_add_f32 v[16:17], v[16:17], 0 op_sel_hi:[1,0]
	v_mov_b32_e32 v18, v28
	v_mov_b32_e32 v19, v30
	v_pk_add_f32 v[16:17], v[16:17], v[18:19]
	s_waitcnt lgkmcnt(0)
	v_mov_b32_e32 v18, v36
	v_mov_b32_e32 v19, v38
	v_mov_b32_e32 v22, v21
	v_pk_add_f32 v[64:65], v[16:17], v[18:19]
	v_pk_add_f32 v[16:17], v[22:23], 0 op_sel_hi:[1,0]
	v_mov_b32_e32 v30, v29
	v_mov_b32_e32 v42, v32
	v_pk_add_f32 v[16:17], v[16:17], v[30:31]
	v_mov_b32_e32 v38, v37
	v_pk_add_f32 v[60:61], v[40:41], v[42:43]
	v_pk_add_f32 v[66:67], v[16:17], v[38:39]
	ds_read_b128 v[16:19], v5 offset:49152
	ds_read_b128 v[20:23], v5 offset:49168
	ds_read_b128 v[24:27], v6
	ds_read_b128 v[28:31], v7
	ds_read_b128 v[32:35], v8
	ds_read_b128 v[36:39], v9
	ds_read_b128 v[40:43], v10
	ds_read_b128 v[44:47], v11
	ds_read_b128 v[48:51], v12
	ds_read_b128 v[52:55], v13
	v_mov_b64_e32 v[68:69], s[8:9]
	v_mad_i64_i32 v[56:57], s[8:9], v56, s78, v[68:69]
	s_waitcnt lgkmcnt(9)
	v_mov_b32_e32 v68, v16
	v_mov_b32_e32 v69, v18
	v_mov_b32_e32 v18, v17
	v_pk_add_f32 v[60:61], v[60:61], v[68:69]
	v_pk_add_f32 v[16:17], v[62:63], v[18:19]
	s_waitcnt lgkmcnt(7)
	v_mov_b32_e32 v18, v24
	v_mov_b32_e32 v19, v26
	v_pk_add_f32 v[18:19], v[60:61], v[18:19]
	v_mov_b32_e32 v26, v25
	s_waitcnt lgkmcnt(5)
	v_mov_b32_e32 v24, v32
	v_mov_b32_e32 v25, v34
	v_pk_add_f32 v[18:19], v[18:19], v[24:25]
	s_waitcnt lgkmcnt(3)
	v_mov_b32_e32 v24, v40
	v_mov_b32_e32 v25, v42
	v_pk_add_f32 v[18:19], v[18:19], v[24:25]
	s_waitcnt lgkmcnt(1)
	v_mov_b32_e32 v24, v48
	v_mov_b32_e32 v25, v50
	v_pk_add_f32 v[18:19], v[18:19], v[24:25]
	v_mov_b32_e32 v24, v20
	v_mov_b32_e32 v25, v22
	v_mov_b32_e32 v22, v21
	v_pk_add_f32 v[24:25], v[64:65], v[24:25]
	v_pk_add_f32 v[20:21], v[66:67], v[22:23]
	v_mov_b32_e32 v22, v28
	v_mov_b32_e32 v23, v30
	v_mov_b32_e32 v30, v29
	v_pk_add_f32 v[16:17], v[16:17], v[26:27]
	v_mov_b32_e32 v34, v33
	v_pk_add_f32 v[22:23], v[24:25], v[22:23]
	v_pk_add_f32 v[20:21], v[20:21], v[30:31]
	v_mov_b32_e32 v24, v36
	v_mov_b32_e32 v25, v38
	v_mov_b32_e32 v38, v37
	v_pk_add_f32 v[16:17], v[16:17], v[34:35]
	v_mov_b32_e32 v42, v41
	v_pk_add_f32 v[22:23], v[22:23], v[24:25]
	v_pk_add_f32 v[20:21], v[20:21], v[38:39]
	v_mov_b32_e32 v24, v44
	v_mov_b32_e32 v25, v46
	v_mov_b32_e32 v46, v45
	v_pk_add_f32 v[16:17], v[16:17], v[42:43]
	v_mov_b32_e32 v50, v49
	v_pk_add_f32 v[22:23], v[22:23], v[24:25]
	v_pk_add_f32 v[20:21], v[20:21], v[46:47]
	s_waitcnt lgkmcnt(0)
	v_mov_b32_e32 v25, v54
	v_mov_b32_e32 v54, v53
	v_pk_add_f32 v[16:17], v[16:17], v[50:51]
	v_mov_b32_e32 v24, v52
	v_pk_add_f32 v[20:21], v[20:21], v[54:55]
	s_waitcnt vmcnt(0)
	v_pk_mul_f32 v[16:17], v[58:59], v[16:17] op_sel_hi:[0,1]
	v_pk_add_f32 v[22:23], v[22:23], v[24:25]
	v_pk_mul_f32 v[20:21], v[58:59], v[20:21] op_sel_hi:[0,1]
	v_pk_mul_f32 v[18:19], v[58:59], v[18:19] op_sel_hi:[0,1]
	v_pk_mul_f32 v[22:23], v[58:59], v[22:23] op_sel_hi:[0,1]
	v_bfe_u32 v3, v21, 16, 1
	v_bfe_u32 v24, v20, 16, 1
	v_bfe_u32 v25, v17, 16, 1
	v_bfe_u32 v26, v16, 16, 1
	v_add3_u32 v16, v16, v26, s90
	v_add3_u32 v17, v17, v25, s90
	v_add3_u32 v20, v20, v24, s90
	v_add3_u32 v3, v21, v3, s90
	v_bfe_u32 v21, v18, 16, 1
	v_bfe_u32 v24, v19, 16, 1
	v_bfe_u32 v25, v22, 16, 1
	v_bfe_u32 v26, v23, 16, 1
	s_ashr_i32 s15, s14, 31
	v_add3_u32 v23, v23, v26, s90
	v_add3_u32 v22, v22, v25, s90
	v_add3_u32 v19, v19, v24, s90
	v_add3_u32 v18, v18, v21, s90
	v_lshl_add_u64 v[56:57], s[14:15], 1, v[56:57]
	v_lshrrev_b32_e32 v21, 16, v18
	v_lshrrev_b32_e32 v24, 16, v19
	v_lshrrev_b32_e32 v18, 16, v22
	v_lshrrev_b32_e32 v19, 16, v23
	s_add_i32 s2, s2, s3
	v_lshl_add_u64 v[56:57], v[0:1], 1, v[56:57]
	v_and_or_b32 v19, v3, s91, v19
	v_and_or_b32 v18, v20, s91, v18
	v_and_or_b32 v17, v17, s91, v24
	v_and_or_b32 v16, v16, s91, v21
	s_cmpk_gt_i32 s2, 0xff
	global_store_dwordx4 v[56:57], v[16:19], off
	s_barrier
	s_cbranch_scc0 .LBB0_496

; #define SG_LD(buf, c) do { _Pragma("unroll") for (int s_ = 0; s_ < 2; ++s_) { \
;             _Pragma("unroll") for (int m = 0; m < 4; ++m) fa[buf][s_][m] = *(const bf16x8*)(ap + (size_t)m * 16 * lda + (c) * 64 + s_ * 32); \
;             _Pragma("unroll") for (int n = 0; n < NT; ++n) fb[buf][s_][n] = *(const bf16x8*)(bp + (size_t)n * 16 * ldb + (c) * 64 + s_ * 32); } } while (0)
; template <int NT, int ACT, int K>
; __device__ __forceinline__ void small_gemm_tile(LAS unsigned char* lds, const bf16* __restrict__ A, const bf16* __restrict__ Bt, bf16* __restrict__ O, int ldc, int lda, int ldb, const float* __restrict__ rs, int m0, int n0, int tid) {
;     ...
;         constexpr int NC2 = KW / 64;
;         bf16x8 fa[3][2][4], fb[3][2][NT];
;     ...
;         SG_LD(0, 0); SG_LD(1, 1);
;         __builtin_amdgcn_sched_barrier(0);
; #pragma unroll
;         for (int c = 0; c < NC2; ++c) {
;             if (c + 2 < NC2) SG_LD((c + 2) % 3, c + 2);
;             __builtin_amdgcn_sched_barrier(0);
; #pragma unroll
;             for (int s_ = 0; s_ < 2; ++s_)
; #pragma unroll
;                 for (int m = 0; m < 4; ++m)
; #pragma unroll
;                     for (int n = 0; n < NT; ++n) acc[m][n] = __builtin_amdgcn_mfma_f32_16x16x32_bf16(fa[c % 3][s_][m], fb[c % 3][s_][n], acc[m][n], 0, 0, 0);
;             __builtin_amdgcn_sched_barrier(0);
;         }
; __global__ void __launch_bounds__(NWAVES * 64, 2) hybrid_fwd(Args args) {
;     ...
;                 else { for (int j = bx; j < (MS / 64) * (DM / 32); j += G) { if (k == 2) small_gemm_tile<2, 0, DM>(lds, (const bf16*)(ws + WS_H + SGRP_BASE + (size_t)(j & 7) * SGRP_BYTES + SGRP_CAT_OFF) - (size_t)(MP + (j & 7) * 64) * DP, Bt, O, OP, DP, DM + WPAD, nullptr, MP + (j & 7) * 64, SMALL_TN(j, DM / 32) * 32, tid); else small_gemm_tile<2, 0, FF>(lds, A, Bt, O, OP, FP, FF + WPAD, nullptr, MP + (j & 7) * 64, SMALL_TN(j, DM / 32) * 32, tid); } }
.LBB0_502:
	s_mov_b64 s[6:7], -1
	s_and_b64 vcc, exec, s[0:1]
	v_lshlrev_b32_e32 v4, 1, v0
	s_cbranch_vccz .LBB0_504
	s_and_b32 s7, s8, 0x1c0
	s_bitset1_b32 s7, 14
	v_readfirstlane_b32 s14, v186
	s_lshl_b32 s6, s9, 2
	s_andn2_b32 s6, s6, 31
	s_ashr_i32 s14, s14, 6
	s_lshl_b32 s16, s14, 10
	s_mov_b32 s17, 0
	s_mul_i32 s100, s7, 0x2080
	s_add_u32 s100, s100, s4
	s_addc_u32 s101, s5, 0
	s_add_u32 s100, s100, s16
	s_addc_u32 s101, s101, 0
	s_add_u32 s16, s16, s10
	s_addc_u32 s17, s17, s11
	s_lshl_b32 vcc_lo, s6, 13
	s_add_u32 s16, s16, vcc_lo
	s_addc_u32 s17, s17, 0
	v_and_b32_e32 v227, 63, v186
	v_lshrrev_b32_e32 v229, 3, v227
	v_and_b32_e32 v230, 7, v227
	v_lshrrev_b32_e32 v231, 1, v229
	v_xor_b32_e32 v230, v230, v231
	v_lshlrev_b32_e32 v230, 4, v230
	v_mul_u32_u24_e32 v231, 0x2080, v229
	v_or_b32_e32 v212, v231, v230
	v_lshl_or_b32 v220, v229, 13, v230
	v_xor_b32_e32 v213, 64, v212
	v_add_u32_e32 v213, 0x10400, v213
	v_xor_b32_e32 v221, 64, v220
	v_add_u32_e32 v221, 0x10000, v221
	v_add_u32_e32 v214, 0x20800, v212
	v_add_u32_e32 v215, 0x20800, v213
	v_add_u32_e32 v216, 0x41000, v212
	v_add_u32_e32 v217, 0x41000, v213
	v_add_u32_e32 v218, 0x61800, v212
	v_add_u32_e32 v219, 0x61800, v213
	v_add_u32_e32 v222, 0x20000, v220
	v_add_u32_e32 v223, 0x20000, v221
	v_and_b32_e32 v229, 15, v227
	v_lshrrev_b32_e32 v230, 4, v227
	v_lshrrev_b32_e32 v231, 1, v229
	v_xor_b32_e32 v230, v230, v231
	v_lshlrev_b32_e32 v230, 4, v230
	v_lshl_or_b32 v224, v229, 7, v230
	v_lshrrev_b32_e32 v231, 6, v186
	v_lshl_add_u32 v224, v231, 14, v224
	v_xor_b32_e32 v225, 64, v224
	v_lshlrev_b32_e32 v226, 4, v227
	v_lshl_add_u32 v226, v231, 14, v226
	global_load_dwordx4 v[40:43], v212, s[100:101]
	global_load_dwordx4 v[44:47], v213, s[100:101]
	global_load_dwordx4 v[48:51], v214, s[100:101]
	global_load_dwordx4 v[52:55], v215, s[100:101]
	global_load_dwordx4 v[56:59], v216, s[100:101]
	global_load_dwordx4 v[60:63], v217, s[100:101]
	global_load_dwordx4 v[64:67], v218, s[100:101]
	global_load_dwordx4 v[68:71], v219, s[100:101]
	global_load_dwordx4 v[72:75], v220, s[16:17]
	global_load_dwordx4 v[76:79], v221, s[16:17]
	global_load_dwordx4 v[80:83], v222, s[16:17]
	global_load_dwordx4 v[84:87], v223, s[16:17]
	global_load_dwordx4 v[88:91], v212, s[100:101] offset:128
	global_load_dwordx4 v[92:95], v213, s[100:101] offset:128
	global_load_dwordx4 v[96:99], v214, s[100:101] offset:128
	global_load_dwordx4 v[100:103], v215, s[100:101] offset:128
	global_load_dwordx4 v[104:107], v216, s[100:101] offset:128
	global_load_dwordx4 v[108:111], v217, s[100:101] offset:128
	global_load_dwordx4 v[112:115], v218, s[100:101] offset:128
	global_load_dwordx4 v[116:119], v219, s[100:101] offset:128
	global_load_dwordx4 v[120:123], v220, s[16:17] offset:128
	global_load_dwordx4 v[124:127], v221, s[16:17] offset:128
	global_load_dwordx4 v[136:139], v222, s[16:17] offset:128
	global_load_dwordx4 v[140:143], v223, s[16:17] offset:128
	s_waitcnt vmcnt(12)
	ds_write_b128 v226, v[40:43]
	ds_write_b128 v226, v[44:47] offset:1024
	ds_write_b128 v226, v[48:51] offset:2048
	ds_write_b128 v226, v[52:55] offset:3072
	ds_write_b128 v226, v[56:59] offset:4096
	ds_write_b128 v226, v[60:63] offset:5120
	ds_write_b128 v226, v[64:67] offset:6144
	ds_write_b128 v226, v[68:71] offset:7168
	ds_write_b128 v226, v[72:75] offset:8192
	ds_write_b128 v226, v[76:79] offset:9216
	ds_write_b128 v226, v[80:83] offset:10240
	ds_write_b128 v226, v[84:87] offset:11264
	s_waitcnt lgkmcnt(0)
	global_load_dwordx4 v[40:43], v212, s[100:101] offset:256
	global_load_dwordx4 v[44:47], v213, s[100:101] offset:256
	global_load_dwordx4 v[48:51], v214, s[100:101] offset:256
	global_load_dwordx4 v[52:55], v215, s[100:101] offset:256
	global_load_dwordx4 v[56:59], v216, s[100:101] offset:256
	global_load_dwordx4 v[60:63], v217, s[100:101] offset:256
	global_load_dwordx4 v[64:67], v218, s[100:101] offset:256
	global_load_dwordx4 v[68:71], v219, s[100:101] offset:256
	global_load_dwordx4 v[72:75], v220, s[16:17] offset:256
	global_load_dwordx4 v[76:79], v221, s[16:17] offset:256
	global_load_dwordx4 v[80:83], v222, s[16:17] offset:256
	global_load_dwordx4 v[84:87], v223, s[16:17] offset:256
	ds_read_b128 v[144:147], v224 offset:0
	ds_read_b128 v[148:151], v225 offset:0
	ds_read_b128 v[154:157], v224 offset:2048
	ds_read_b128 v[158:161], v225 offset:2048
	ds_read_b128 v[162:165], v224 offset:4096
	ds_read_b128 v[188:191], v225 offset:4096
	ds_read_b128 v[192:195], v224 offset:6144
	ds_read_b128 v[196:199], v225 offset:6144
	ds_read_b128 v[200:203], v224 offset:8192
	ds_read_b128 v[204:207], v225 offset:8192
	ds_read_b128 v[208:211], v224 offset:10240
	ds_read_b128 v[232:235], v225 offset:10240
	s_waitcnt lgkmcnt(0)
	v_mfma_f32_16x16x32_bf16 v[36:39], v[144:147], v[200:203], 0
	v_mfma_f32_16x16x32_bf16 v[8:11], v[144:147], v[208:211], 0
	v_mfma_f32_16x16x32_bf16 v[12:15], v[154:157], v[200:203], 0
	v_mfma_f32_16x16x32_bf16 v[16:19], v[154:157], v[208:211], 0
	v_mfma_f32_16x16x32_bf16 v[20:23], v[162:165], v[200:203], 0
	v_mfma_f32_16x16x32_bf16 v[24:27], v[162:165], v[208:211], 0
	v_mfma_f32_16x16x32_bf16 v[28:31], v[192:195], v[200:203], 0
	v_mfma_f32_16x16x32_bf16 v[32:35], v[192:195], v[208:211], 0
	v_mfma_f32_16x16x32_bf16 v[36:39], v[148:151], v[204:207], v[36:39]
	v_mfma_f32_16x16x32_bf16 v[8:11], v[148:151], v[232:235], v[8:11]
	v_mfma_f32_16x16x32_bf16 v[12:15], v[158:161], v[204:207], v[12:15]
	v_mfma_f32_16x16x32_bf16 v[16:19], v[158:161], v[232:235], v[16:19]
	v_mfma_f32_16x16x32_bf16 v[20:23], v[188:191], v[204:207], v[20:23]
	v_mfma_f32_16x16x32_bf16 v[24:27], v[188:191], v[232:235], v[24:27]
	v_mfma_f32_16x16x32_bf16 v[28:31], v[196:199], v[204:207], v[28:31]
	v_mfma_f32_16x16x32_bf16 v[32:35], v[196:199], v[232:235], v[32:35]
	s_waitcnt vmcnt(12)
; #define SG_LD(buf, c) do { _Pragma("unroll") for (int s_ = 0; s_ < 2; ++s_) { \
;             _Pragma("unroll") for (int m = 0; m < 4; ++m) fa[buf][s_][m] = *(const bf16x8*)(ap + (size_t)m * 16 * lda + (c) * 64 + s_ * 32); \
;             _Pragma("unroll") for (int n = 0; n < NT; ++n) fb[buf][s_][n] = *(const bf16x8*)(bp + (size_t)n * 16 * ldb + (c) * 64 + s_ * 32); } } while (0)
; template <int NT, int ACT, int K>
; __device__ __forceinline__ void small_gemm_tile(LAS unsigned char* lds, const bf16* __restrict__ A, const bf16* __restrict__ Bt, bf16* __restrict__ O, int ldc, int lda, int ldb, const float* __restrict__ rs, int m0, int n0, int tid) {
;     ...
;         SG_LD(0, 0); SG_LD(1, 1);
;         __builtin_amdgcn_sched_barrier(0);
; #pragma unroll
;         for (int c = 0; c < NC2; ++c) {
;             if (c + 2 < NC2) SG_LD((c + 2) % 3, c + 2);
;             __builtin_amdgcn_sched_barrier(0);
; #pragma unroll
;             for (int s_ = 0; s_ < 2; ++s_)
; #pragma unroll
;                 for (int m = 0; m < 4; ++m)
; #pragma unroll
;                     for (int n = 0; n < NT; ++n) acc[m][n] = __builtin_amdgcn_mfma_f32_16x16x32_bf16(fa[c % 3][s_][m], fb[c % 3][s_][n], acc[m][n], 0, 0, 0);
;             __builtin_amdgcn_sched_barrier(0);
;         }
	ds_write_b128 v226, v[88:91]
	ds_write_b128 v226, v[92:95] offset:1024
	ds_write_b128 v226, v[96:99] offset:2048
	ds_write_b128 v226, v[100:103] offset:3072
	ds_write_b128 v226, v[104:107] offset:4096
	ds_write_b128 v226, v[108:111] offset:5120
	ds_write_b128 v226, v[112:115] offset:6144
	ds_write_b128 v226, v[116:119] offset:7168
	ds_write_b128 v226, v[120:123] offset:8192
	ds_write_b128 v226, v[124:127] offset:9216
	ds_write_b128 v226, v[136:139] offset:10240
	ds_write_b128 v226, v[140:143] offset:11264
	s_waitcnt lgkmcnt(0)
	global_load_dwordx4 v[88:91], v212, s[100:101] offset:384
	global_load_dwordx4 v[92:95], v213, s[100:101] offset:384
	global_load_dwordx4 v[96:99], v214, s[100:101] offset:384
	global_load_dwordx4 v[100:103], v215, s[100:101] offset:384
	global_load_dwordx4 v[104:107], v216, s[100:101] offset:384
	global_load_dwordx4 v[108:111], v217, s[100:101] offset:384
	global_load_dwordx4 v[112:115], v218, s[100:101] offset:384
	global_load_dwordx4 v[116:119], v219, s[100:101] offset:384
	global_load_dwordx4 v[120:123], v220, s[16:17] offset:384
	global_load_dwordx4 v[124:127], v221, s[16:17] offset:384
	global_load_dwordx4 v[136:139], v222, s[16:17] offset:384
	global_load_dwordx4 v[140:143], v223, s[16:17] offset:384
	ds_read_b128 v[144:147], v224 offset:0
	ds_read_b128 v[148:151], v225 offset:0
	ds_read_b128 v[154:157], v224 offset:2048
	ds_read_b128 v[158:161], v225 offset:2048
	ds_read_b128 v[162:165], v224 offset:4096
	ds_read_b128 v[188:191], v225 offset:4096
	ds_read_b128 v[192:195], v224 offset:6144
	ds_read_b128 v[196:199], v225 offset:6144
	ds_read_b128 v[200:203], v224 offset:8192
	ds_read_b128 v[204:207], v225 offset:8192
	ds_read_b128 v[208:211], v224 offset:10240
	ds_read_b128 v[232:235], v225 offset:10240
	s_waitcnt lgkmcnt(0)
	v_mfma_f32_16x16x32_bf16 v[36:39], v[144:147], v[200:203], v[36:39]
	v_mfma_f32_16x16x32_bf16 v[8:11], v[144:147], v[208:211], v[8:11]
	v_mfma_f32_16x16x32_bf16 v[12:15], v[154:157], v[200:203], v[12:15]
	v_mfma_f32_16x16x32_bf16 v[16:19], v[154:157], v[208:211], v[16:19]
	v_mfma_f32_16x16x32_bf16 v[20:23], v[162:165], v[200:203], v[20:23]
	v_mfma_f32_16x16x32_bf16 v[24:27], v[162:165], v[208:211], v[24:27]
	v_mfma_f32_16x16x32_bf16 v[28:31], v[192:195], v[200:203], v[28:31]
	v_mfma_f32_16x16x32_bf16 v[32:35], v[192:195], v[208:211], v[32:35]
	v_mfma_f32_16x16x32_bf16 v[36:39], v[148:151], v[204:207], v[36:39]
	v_mfma_f32_16x16x32_bf16 v[8:11], v[148:151], v[232:235], v[8:11]
	v_mfma_f32_16x16x32_bf16 v[12:15], v[158:161], v[204:207], v[12:15]
	v_mfma_f32_16x16x32_bf16 v[16:19], v[158:161], v[232:235], v[16:19]
	v_mfma_f32_16x16x32_bf16 v[20:23], v[188:191], v[204:207], v[20:23]
	v_mfma_f32_16x16x32_bf16 v[24:27], v[188:191], v[232:235], v[24:27]
	v_mfma_f32_16x16x32_bf16 v[28:31], v[196:199], v[204:207], v[28:31]
	v_mfma_f32_16x16x32_bf16 v[32:35], v[196:199], v[232:235], v[32:35]
	s_waitcnt vmcnt(12)
	ds_write_b128 v226, v[40:43]
	ds_write_b128 v226, v[44:47] offset:1024
	ds_write_b128 v226, v[48:51] offset:2048
	ds_write_b128 v226, v[52:55] offset:3072
	ds_write_b128 v226, v[56:59] offset:4096
	ds_write_b128 v226, v[60:63] offset:5120
	ds_write_b128 v226, v[64:67] offset:6144
	ds_write_b128 v226, v[68:71] offset:7168
	ds_write_b128 v226, v[72:75] offset:8192
	ds_write_b128 v226, v[76:79] offset:9216
	ds_write_b128 v226, v[80:83] offset:10240
	ds_write_b128 v226, v[84:87] offset:11264
	s_waitcnt lgkmcnt(0)
	global_load_dwordx4 v[40:43], v212, s[100:101] offset:512
	global_load_dwordx4 v[44:47], v213, s[100:101] offset:512
	global_load_dwordx4 v[48:51], v214, s[100:101] offset:512
	global_load_dwordx4 v[52:55], v215, s[100:101] offset:512
	global_load_dwordx4 v[56:59], v216, s[100:101] offset:512
	global_load_dwordx4 v[60:63], v217, s[100:101] offset:512
	global_load_dwordx4 v[64:67], v218, s[100:101] offset:512
	global_load_dwordx4 v[68:71], v219, s[100:101] offset:512
	global_load_dwordx4 v[72:75], v220, s[16:17] offset:512
	global_load_dwordx4 v[76:79], v221, s[16:17] offset:512
	global_load_dwordx4 v[80:83], v222, s[16:17] offset:512
	global_load_dwordx4 v[84:87], v223, s[16:17] offset:512
	ds_read_b128 v[144:147], v224 offset:0
	ds_read_b128 v[148:151], v225 offset:0
	ds_read_b128 v[154:157], v224 offset:2048
	ds_read_b128 v[158:161], v225 offset:2048
	ds_read_b128 v[162:165], v224 offset:4096
	ds_read_b128 v[188:191], v225 offset:4096
	ds_read_b128 v[192:195], v224 offset:6144
	ds_read_b128 v[196:199], v225 offset:6144
	ds_read_b128 v[200:203], v224 offset:8192
	ds_read_b128 v[204:207], v225 offset:8192
	ds_read_b128 v[208:211], v224 offset:10240
	ds_read_b128 v[232:235], v225 offset:10240
	s_waitcnt lgkmcnt(0)
	v_mfma_f32_16x16x32_bf16 v[36:39], v[144:147], v[200:203], v[36:39]
	v_mfma_f32_16x16x32_bf16 v[8:11], v[144:147], v[208:211], v[8:11]
	v_mfma_f32_16x16x32_bf16 v[12:15], v[154:157], v[200:203], v[12:15]
	v_mfma_f32_16x16x32_bf16 v[16:19], v[154:157], v[208:211], v[16:19]
	v_mfma_f32_16x16x32_bf16 v[20:23], v[162:165], v[200:203], v[20:23]
	v_mfma_f32_16x16x32_bf16 v[24:27], v[162:165], v[208:211], v[24:27]
	v_mfma_f32_16x16x32_bf16 v[28:31], v[192:195], v[200:203], v[28:31]
	v_mfma_f32_16x16x32_bf16 v[32:35], v[192:195], v[208:211], v[32:35]
	v_mfma_f32_16x16x32_bf16 v[36:39], v[148:151], v[204:207], v[36:39]
	v_mfma_f32_16x16x32_bf16 v[8:11], v[148:151], v[232:235], v[8:11]
	v_mfma_f32_16x16x32_bf16 v[12:15], v[158:161], v[204:207], v[12:15]
	v_mfma_f32_16x16x32_bf16 v[16:19], v[158:161], v[232:235], v[16:19]
	v_mfma_f32_16x16x32_bf16 v[20:23], v[188:191], v[204:207], v[20:23]
	v_mfma_f32_16x16x32_bf16 v[24:27], v[188:191], v[232:235], v[24:27]
	v_mfma_f32_16x16x32_bf16 v[28:31], v[196:199], v[204:207], v[28:31]
	v_mfma_f32_16x16x32_bf16 v[32:35], v[196:199], v[232:235], v[32:35]
	s_waitcnt vmcnt(12)
; #define SG_LD(buf, c) do { _Pragma("unroll") for (int s_ = 0; s_ < 2; ++s_) { \
;             _Pragma("unroll") for (int m = 0; m < 4; ++m) fa[buf][s_][m] = *(const bf16x8*)(ap + (size_t)m * 16 * lda + (c) * 64 + s_ * 32); \
;             _Pragma("unroll") for (int n = 0; n < NT; ++n) fb[buf][s_][n] = *(const bf16x8*)(bp + (size_t)n * 16 * ldb + (c) * 64 + s_ * 32); } } while (0)
; template <int NT, int ACT, int K>
; __device__ __forceinline__ void small_gemm_tile(LAS unsigned char* lds, const bf16* __restrict__ A, const bf16* __restrict__ Bt, bf16* __restrict__ O, int ldc, int lda, int ldb, const float* __restrict__ rs, int m0, int n0, int tid) {
;     ...
;         SG_LD(0, 0); SG_LD(1, 1);
;         __builtin_amdgcn_sched_barrier(0);
; #pragma unroll
;         for (int c = 0; c < NC2; ++c) {
;             if (c + 2 < NC2) SG_LD((c + 2) % 3, c + 2);
;             __builtin_amdgcn_sched_barrier(0);
; #pragma unroll
;             for (int s_ = 0; s_ < 2; ++s_)
; #pragma unroll
;                 for (int m = 0; m < 4; ++m)
; #pragma unroll
;                     for (int n = 0; n < NT; ++n) acc[m][n] = __builtin_amdgcn_mfma_f32_16x16x32_bf16(fa[c % 3][s_][m], fb[c % 3][s_][n], acc[m][n], 0, 0, 0);
;             __builtin_amdgcn_sched_barrier(0);
;         }
	ds_write_b128 v226, v[88:91]
	ds_write_b128 v226, v[92:95] offset:1024
	ds_write_b128 v226, v[96:99] offset:2048
	ds_write_b128 v226, v[100:103] offset:3072
	ds_write_b128 v226, v[104:107] offset:4096
	ds_write_b128 v226, v[108:111] offset:5120
	ds_write_b128 v226, v[112:115] offset:6144
	ds_write_b128 v226, v[116:119] offset:7168
	ds_write_b128 v226, v[120:123] offset:8192
	ds_write_b128 v226, v[124:127] offset:9216
	ds_write_b128 v226, v[136:139] offset:10240
	ds_write_b128 v226, v[140:143] offset:11264
	s_waitcnt lgkmcnt(0)
	global_load_dwordx4 v[88:91], v212, s[100:101] offset:640
	global_load_dwordx4 v[92:95], v213, s[100:101] offset:640
	global_load_dwordx4 v[96:99], v214, s[100:101] offset:640
	global_load_dwordx4 v[100:103], v215, s[100:101] offset:640
	global_load_dwordx4 v[104:107], v216, s[100:101] offset:640
	global_load_dwordx4 v[108:111], v217, s[100:101] offset:640
	global_load_dwordx4 v[112:115], v218, s[100:101] offset:640
	global_load_dwordx4 v[116:119], v219, s[100:101] offset:640
	global_load_dwordx4 v[120:123], v220, s[16:17] offset:640
	global_load_dwordx4 v[124:127], v221, s[16:17] offset:640
	global_load_dwordx4 v[136:139], v222, s[16:17] offset:640
	global_load_dwordx4 v[140:143], v223, s[16:17] offset:640
	ds_read_b128 v[144:147], v224 offset:0
	ds_read_b128 v[148:151], v225 offset:0
	ds_read_b128 v[154:157], v224 offset:2048
	ds_read_b128 v[158:161], v225 offset:2048
	ds_read_b128 v[162:165], v224 offset:4096
	ds_read_b128 v[188:191], v225 offset:4096
	ds_read_b128 v[192:195], v224 offset:6144
	ds_read_b128 v[196:199], v225 offset:6144
	ds_read_b128 v[200:203], v224 offset:8192
	ds_read_b128 v[204:207], v225 offset:8192
	ds_read_b128 v[208:211], v224 offset:10240
	ds_read_b128 v[232:235], v225 offset:10240
	s_waitcnt lgkmcnt(0)
	v_mfma_f32_16x16x32_bf16 v[36:39], v[144:147], v[200:203], v[36:39]
	v_mfma_f32_16x16x32_bf16 v[8:11], v[144:147], v[208:211], v[8:11]
	v_mfma_f32_16x16x32_bf16 v[12:15], v[154:157], v[200:203], v[12:15]
	v_mfma_f32_16x16x32_bf16 v[16:19], v[154:157], v[208:211], v[16:19]
	v_mfma_f32_16x16x32_bf16 v[20:23], v[162:165], v[200:203], v[20:23]
	v_mfma_f32_16x16x32_bf16 v[24:27], v[162:165], v[208:211], v[24:27]
	v_mfma_f32_16x16x32_bf16 v[28:31], v[192:195], v[200:203], v[28:31]
	v_mfma_f32_16x16x32_bf16 v[32:35], v[192:195], v[208:211], v[32:35]
	v_mfma_f32_16x16x32_bf16 v[36:39], v[148:151], v[204:207], v[36:39]
	v_mfma_f32_16x16x32_bf16 v[8:11], v[148:151], v[232:235], v[8:11]
	v_mfma_f32_16x16x32_bf16 v[12:15], v[158:161], v[204:207], v[12:15]
	v_mfma_f32_16x16x32_bf16 v[16:19], v[158:161], v[232:235], v[16:19]
	v_mfma_f32_16x16x32_bf16 v[20:23], v[188:191], v[204:207], v[20:23]
	v_mfma_f32_16x16x32_bf16 v[24:27], v[188:191], v[232:235], v[24:27]
	v_mfma_f32_16x16x32_bf16 v[28:31], v[196:199], v[204:207], v[28:31]
	v_mfma_f32_16x16x32_bf16 v[32:35], v[196:199], v[232:235], v[32:35]
	s_waitcnt vmcnt(12)
	ds_write_b128 v226, v[40:43]
	ds_write_b128 v226, v[44:47] offset:1024
	ds_write_b128 v226, v[48:51] offset:2048
	ds_write_b128 v226, v[52:55] offset:3072
	ds_write_b128 v226, v[56:59] offset:4096
	ds_write_b128 v226, v[60:63] offset:5120
	ds_write_b128 v226, v[64:67] offset:6144
	ds_write_b128 v226, v[68:71] offset:7168
	ds_write_b128 v226, v[72:75] offset:8192
	ds_write_b128 v226, v[76:79] offset:9216
	ds_write_b128 v226, v[80:83] offset:10240
	ds_write_b128 v226, v[84:87] offset:11264
	s_waitcnt lgkmcnt(0)
	global_load_dwordx4 v[40:43], v212, s[100:101] offset:768
	global_load_dwordx4 v[44:47], v213, s[100:101] offset:768
	global_load_dwordx4 v[48:51], v214, s[100:101] offset:768
	global_load_dwordx4 v[52:55], v215, s[100:101] offset:768
	global_load_dwordx4 v[56:59], v216, s[100:101] offset:768
	global_load_dwordx4 v[60:63], v217, s[100:101] offset:768
	global_load_dwordx4 v[64:67], v218, s[100:101] offset:768
	global_load_dwordx4 v[68:71], v219, s[100:101] offset:768
	global_load_dwordx4 v[72:75], v220, s[16:17] offset:768
	global_load_dwordx4 v[76:79], v221, s[16:17] offset:768
	global_load_dwordx4 v[80:83], v222, s[16:17] offset:768
	global_load_dwordx4 v[84:87], v223, s[16:17] offset:768
	ds_read_b128 v[144:147], v224 offset:0
	ds_read_b128 v[148:151], v225 offset:0
	ds_read_b128 v[154:157], v224 offset:2048
	ds_read_b128 v[158:161], v225 offset:2048
	ds_read_b128 v[162:165], v224 offset:4096
	ds_read_b128 v[188:191], v225 offset:4096
	ds_read_b128 v[192:195], v224 offset:6144
	ds_read_b128 v[196:199], v225 offset:6144
	ds_read_b128 v[200:203], v224 offset:8192
	ds_read_b128 v[204:207], v225 offset:8192
	ds_read_b128 v[208:211], v224 offset:10240
	ds_read_b128 v[232:235], v225 offset:10240
	s_waitcnt lgkmcnt(0)
	v_mfma_f32_16x16x32_bf16 v[36:39], v[144:147], v[200:203], v[36:39]
	v_mfma_f32_16x16x32_bf16 v[8:11], v[144:147], v[208:211], v[8:11]
	v_mfma_f32_16x16x32_bf16 v[12:15], v[154:157], v[200:203], v[12:15]
	v_mfma_f32_16x16x32_bf16 v[16:19], v[154:157], v[208:211], v[16:19]
	v_mfma_f32_16x16x32_bf16 v[20:23], v[162:165], v[200:203], v[20:23]
	v_mfma_f32_16x16x32_bf16 v[24:27], v[162:165], v[208:211], v[24:27]
	v_mfma_f32_16x16x32_bf16 v[28:31], v[192:195], v[200:203], v[28:31]
	v_mfma_f32_16x16x32_bf16 v[32:35], v[192:195], v[208:211], v[32:35]
	v_mfma_f32_16x16x32_bf16 v[36:39], v[148:151], v[204:207], v[36:39]
	v_mfma_f32_16x16x32_bf16 v[8:11], v[148:151], v[232:235], v[8:11]
	v_mfma_f32_16x16x32_bf16 v[12:15], v[158:161], v[204:207], v[12:15]
	v_mfma_f32_16x16x32_bf16 v[16:19], v[158:161], v[232:235], v[16:19]
	v_mfma_f32_16x16x32_bf16 v[20:23], v[188:191], v[204:207], v[20:23]
	v_mfma_f32_16x16x32_bf16 v[24:27], v[188:191], v[232:235], v[24:27]
	v_mfma_f32_16x16x32_bf16 v[28:31], v[196:199], v[204:207], v[28:31]
	v_mfma_f32_16x16x32_bf16 v[32:35], v[196:199], v[232:235], v[32:35]
	s_waitcnt vmcnt(12)
; #define SG_LD(buf, c) do { _Pragma("unroll") for (int s_ = 0; s_ < 2; ++s_) { \
;             _Pragma("unroll") for (int m = 0; m < 4; ++m) fa[buf][s_][m] = *(const bf16x8*)(ap + (size_t)m * 16 * lda + (c) * 64 + s_ * 32); \
;             _Pragma("unroll") for (int n = 0; n < NT; ++n) fb[buf][s_][n] = *(const bf16x8*)(bp + (size_t)n * 16 * ldb + (c) * 64 + s_ * 32); } } while (0)
; template <int NT, int ACT, int K>
; __device__ __forceinline__ void small_gemm_tile(LAS unsigned char* lds, const bf16* __restrict__ A, const bf16* __restrict__ Bt, bf16* __restrict__ O, int ldc, int lda, int ldb, const float* __restrict__ rs, int m0, int n0, int tid) {
;     ...
;         SG_LD(0, 0); SG_LD(1, 1);
;         __builtin_amdgcn_sched_barrier(0);
; #pragma unroll
;         for (int c = 0; c < NC2; ++c) {
;             if (c + 2 < NC2) SG_LD((c + 2) % 3, c + 2);
;             __builtin_amdgcn_sched_barrier(0);
; #pragma unroll
;             for (int s_ = 0; s_ < 2; ++s_)
; #pragma unroll
;                 for (int m = 0; m < 4; ++m)
; #pragma unroll
;                     for (int n = 0; n < NT; ++n) acc[m][n] = __builtin_amdgcn_mfma_f32_16x16x32_bf16(fa[c % 3][s_][m], fb[c % 3][s_][n], acc[m][n], 0, 0, 0);
;             __builtin_amdgcn_sched_barrier(0);
;         }
	ds_write_b128 v226, v[88:91]
	ds_write_b128 v226, v[92:95] offset:1024
	ds_write_b128 v226, v[96:99] offset:2048
	ds_write_b128 v226, v[100:103] offset:3072
	ds_write_b128 v226, v[104:107] offset:4096
	ds_write_b128 v226, v[108:111] offset:5120
	ds_write_b128 v226, v[112:115] offset:6144
	ds_write_b128 v226, v[116:119] offset:7168
	ds_write_b128 v226, v[120:123] offset:8192
	ds_write_b128 v226, v[124:127] offset:9216
	ds_write_b128 v226, v[136:139] offset:10240
	ds_write_b128 v226, v[140:143] offset:11264
	s_waitcnt lgkmcnt(0)
	global_load_dwordx4 v[88:91], v212, s[100:101] offset:896
	global_load_dwordx4 v[92:95], v213, s[100:101] offset:896
	global_load_dwordx4 v[96:99], v214, s[100:101] offset:896
	global_load_dwordx4 v[100:103], v215, s[100:101] offset:896
	global_load_dwordx4 v[104:107], v216, s[100:101] offset:896
	global_load_dwordx4 v[108:111], v217, s[100:101] offset:896
	global_load_dwordx4 v[112:115], v218, s[100:101] offset:896
	global_load_dwordx4 v[116:119], v219, s[100:101] offset:896
	global_load_dwordx4 v[120:123], v220, s[16:17] offset:896
	global_load_dwordx4 v[124:127], v221, s[16:17] offset:896
	global_load_dwordx4 v[136:139], v222, s[16:17] offset:896
	global_load_dwordx4 v[140:143], v223, s[16:17] offset:896
	ds_read_b128 v[144:147], v224 offset:0
	ds_read_b128 v[148:151], v225 offset:0
	ds_read_b128 v[154:157], v224 offset:2048
	ds_read_b128 v[158:161], v225 offset:2048
	ds_read_b128 v[162:165], v224 offset:4096
	ds_read_b128 v[188:191], v225 offset:4096
	ds_read_b128 v[192:195], v224 offset:6144
	ds_read_b128 v[196:199], v225 offset:6144
	ds_read_b128 v[200:203], v224 offset:8192
	ds_read_b128 v[204:207], v225 offset:8192
	ds_read_b128 v[208:211], v224 offset:10240
	ds_read_b128 v[232:235], v225 offset:10240
	s_waitcnt lgkmcnt(0)
	v_mfma_f32_16x16x32_bf16 v[36:39], v[144:147], v[200:203], v[36:39]
	v_mfma_f32_16x16x32_bf16 v[8:11], v[144:147], v[208:211], v[8:11]
	v_mfma_f32_16x16x32_bf16 v[12:15], v[154:157], v[200:203], v[12:15]
	v_mfma_f32_16x16x32_bf16 v[16:19], v[154:157], v[208:211], v[16:19]
	v_mfma_f32_16x16x32_bf16 v[20:23], v[162:165], v[200:203], v[20:23]
	v_mfma_f32_16x16x32_bf16 v[24:27], v[162:165], v[208:211], v[24:27]
	v_mfma_f32_16x16x32_bf16 v[28:31], v[192:195], v[200:203], v[28:31]
	v_mfma_f32_16x16x32_bf16 v[32:35], v[192:195], v[208:211], v[32:35]
	v_mfma_f32_16x16x32_bf16 v[36:39], v[148:151], v[204:207], v[36:39]
	v_mfma_f32_16x16x32_bf16 v[8:11], v[148:151], v[232:235], v[8:11]
	v_mfma_f32_16x16x32_bf16 v[12:15], v[158:161], v[204:207], v[12:15]
	v_mfma_f32_16x16x32_bf16 v[16:19], v[158:161], v[232:235], v[16:19]
	v_mfma_f32_16x16x32_bf16 v[20:23], v[188:191], v[204:207], v[20:23]
	v_mfma_f32_16x16x32_bf16 v[24:27], v[188:191], v[232:235], v[24:27]
	v_mfma_f32_16x16x32_bf16 v[28:31], v[196:199], v[204:207], v[28:31]
	v_mfma_f32_16x16x32_bf16 v[32:35], v[196:199], v[232:235], v[32:35]
	s_waitcnt vmcnt(12)
	ds_write_b128 v226, v[40:43]
	ds_write_b128 v226, v[44:47] offset:1024
	ds_write_b128 v226, v[48:51] offset:2048
	ds_write_b128 v226, v[52:55] offset:3072
	ds_write_b128 v226, v[56:59] offset:4096
	ds_write_b128 v226, v[60:63] offset:5120
	ds_write_b128 v226, v[64:67] offset:6144
	ds_write_b128 v226, v[68:71] offset:7168
	ds_write_b128 v226, v[72:75] offset:8192
	ds_write_b128 v226, v[76:79] offset:9216
	ds_write_b128 v226, v[80:83] offset:10240
	ds_write_b128 v226, v[84:87] offset:11264
	s_waitcnt lgkmcnt(0)
	ds_read_b128 v[144:147], v224 offset:0
	ds_read_b128 v[148:151], v225 offset:0
	ds_read_b128 v[154:157], v224 offset:2048
	ds_read_b128 v[158:161], v225 offset:2048
	ds_read_b128 v[162:165], v224 offset:4096
	ds_read_b128 v[188:191], v225 offset:4096
	ds_read_b128 v[192:195], v224 offset:6144
	ds_read_b128 v[196:199], v225 offset:6144
	ds_read_b128 v[200:203], v224 offset:8192
	ds_read_b128 v[204:207], v225 offset:8192
	ds_read_b128 v[208:211], v224 offset:10240
	ds_read_b128 v[232:235], v225 offset:10240
	s_waitcnt lgkmcnt(0)
	v_mfma_f32_16x16x32_bf16 v[36:39], v[144:147], v[200:203], v[36:39]
	v_mfma_f32_16x16x32_bf16 v[8:11], v[144:147], v[208:211], v[8:11]
	v_mfma_f32_16x16x32_bf16 v[12:15], v[154:157], v[200:203], v[12:15]
	v_mfma_f32_16x16x32_bf16 v[16:19], v[154:157], v[208:211], v[16:19]
	v_mfma_f32_16x16x32_bf16 v[20:23], v[162:165], v[200:203], v[20:23]
	v_mfma_f32_16x16x32_bf16 v[24:27], v[162:165], v[208:211], v[24:27]
	v_mfma_f32_16x16x32_bf16 v[28:31], v[192:195], v[200:203], v[28:31]
	v_mfma_f32_16x16x32_bf16 v[32:35], v[192:195], v[208:211], v[32:35]
	v_mfma_f32_16x16x32_bf16 v[36:39], v[148:151], v[204:207], v[36:39]
	v_mfma_f32_16x16x32_bf16 v[8:11], v[148:151], v[232:235], v[8:11]
	v_mfma_f32_16x16x32_bf16 v[12:15], v[158:161], v[204:207], v[12:15]
	v_mfma_f32_16x16x32_bf16 v[16:19], v[158:161], v[232:235], v[16:19]
	v_mfma_f32_16x16x32_bf16 v[20:23], v[188:191], v[204:207], v[20:23]
	v_mfma_f32_16x16x32_bf16 v[24:27], v[188:191], v[232:235], v[24:27]
	v_mfma_f32_16x16x32_bf16 v[28:31], v[196:199], v[204:207], v[28:31]
	v_mfma_f32_16x16x32_bf16 v[32:35], v[196:199], v[232:235], v[32:35]
	s_waitcnt vmcnt(0)
	ds_write_b128 v226, v[88:91]
	ds_write_b128 v226, v[92:95] offset:1024
	ds_write_b128 v226, v[96:99] offset:2048
	ds_write_b128 v226, v[100:103] offset:3072
	ds_write_b128 v226, v[104:107] offset:4096
	ds_write_b128 v226, v[108:111] offset:5120
	ds_write_b128 v226, v[112:115] offset:6144
	ds_write_b128 v226, v[116:119] offset:7168
	ds_write_b128 v226, v[120:123] offset:8192
	ds_write_b128 v226, v[124:127] offset:9216
	ds_write_b128 v226, v[136:139] offset:10240
	ds_write_b128 v226, v[140:143] offset:11264
	s_waitcnt lgkmcnt(0)
	ds_read_b128 v[144:147], v224 offset:0
	ds_read_b128 v[148:151], v225 offset:0
	ds_read_b128 v[154:157], v224 offset:2048
	ds_read_b128 v[158:161], v225 offset:2048
	ds_read_b128 v[162:165], v224 offset:4096
	ds_read_b128 v[188:191], v225 offset:4096
	ds_read_b128 v[192:195], v224 offset:6144
	ds_read_b128 v[196:199], v225 offset:6144
	ds_read_b128 v[200:203], v224 offset:8192
	ds_read_b128 v[204:207], v225 offset:8192
	ds_read_b128 v[208:211], v224 offset:10240
	ds_read_b128 v[232:235], v225 offset:10240
	s_waitcnt lgkmcnt(0)
	s_barrier
; #define LAS __attribute__((address_space(3)))
; __device__ __forceinline__ unsigned pk2(float lo, float hi) { return f2bf(lo) | (f2bf(hi) << 16); }
; template <int NT, int ACT, int K>
; __device__ __forceinline__ void small_gemm_tile(LAS unsigned char* lds, const bf16* __restrict__ A, const bf16* __restrict__ Bt, bf16* __restrict__ O, int ldc, int lda, int ldb, const float* __restrict__ rs, int m0, int n0, int tid) {
;     ...
;             for (int s_ = 0; s_ < 2; ++s_)
; #pragma unroll
;                 for (int m = 0; m < 4; ++m)
; #pragma unroll
;                     for (int n = 0; n < NT; ++n) acc[m][n] = __builtin_amdgcn_mfma_f32_16x16x32_bf16(fa[c % 3][s_][m], fb[c % 3][s_][n], acc[m][n], 0, 0, 0);
;             __builtin_amdgcn_sched_barrier(0);
;         }
;     ...
;     }
;     LAS float* P = (LAS float*)lds + wave * (64 * NC);
; #pragma unroll
;     for (int m = 0; m < 4; ++m)
; #pragma unroll
;         for (int n = 0; n < NT; ++n)
; #pragma unroll
;             for (int i = 0; i < 4; ++i) P[(m * 16 + fq * 4 + i) * NC + n * 16 + fr] = acc[m][n][i];
;     __syncthreads();
;     constexpr int EPT = 64 * NC / 512;
;     const int e0 = tid * EPT, row = e0 / NC, col = e0 % NC;
;     float r[EPT];
; #pragma unroll
;     for (int j = 0; j < EPT; ++j) r[j] = 0.f;
; #pragma unroll
;     for (int w = 0; w < 8; ++w) { const LAS f32x4* q = (const LAS f32x4*)((LAS float*)lds + w * (64 * NC) + e0);
; #pragma unroll
;         for (int j = 0; j < EPT / 4; ++j) { const f32x4 v = q[j]; r[4 * j] += v[0]; r[4 * j + 1] += v[1]; r[4 * j + 2] += v[2]; r[4 * j + 3] += v[3]; } }
;     if (rs) { const float sc = rs[m0 + row];
; #pragma unroll
;         for (int j = 0; j < EPT; ++j) r[j] *= sc; }
;     if (ACT == 1) {
; #pragma unroll
;         for (int j = 0; j < EPT; ++j) { const float t = fmaxf(r[j], 0.f); r[j] = t * t; } }
;     bf16* op = O + (size_t)(m0 + row) * ldc + n0 + col;
;     if (EPT == 8) { v4u w; w.x = pk2(r[0], r[1]); w.y = pk2(r[2], r[3]); w.z = pk2(r[4 % EPT], r[5 % EPT]); w.w = pk2(r[6 % EPT], r[7 % EPT]); *(v4u*)op = w; }
;     else { v2u w; w.x = pk2(r[0], r[1]); w.y = pk2(r[2], r[3]); *(v2u*)op = w; }
;     __syncthreads();
	v_mfma_f32_16x16x32_bf16 v[36:39], v[144:147], v[200:203], v[36:39]
	v_mfma_f32_16x16x32_bf16 v[8:11], v[144:147], v[208:211], v[8:11]
	v_mfma_f32_16x16x32_bf16 v[12:15], v[154:157], v[200:203], v[12:15]
	v_mfma_f32_16x16x32_bf16 v[16:19], v[154:157], v[208:211], v[16:19]
	v_mfma_f32_16x16x32_bf16 v[20:23], v[162:165], v[200:203], v[20:23]
	v_mfma_f32_16x16x32_bf16 v[24:27], v[162:165], v[208:211], v[24:27]
	v_mfma_f32_16x16x32_bf16 v[28:31], v[192:195], v[200:203], v[28:31]
	v_mfma_f32_16x16x32_bf16 v[32:35], v[192:195], v[208:211], v[32:35]
	v_mfma_f32_16x16x32_bf16 v[36:39], v[148:151], v[204:207], v[36:39]
	v_mfma_f32_16x16x32_bf16 v[8:11], v[148:151], v[232:235], v[8:11]
	v_mfma_f32_16x16x32_bf16 v[12:15], v[158:161], v[204:207], v[12:15]
	v_mfma_f32_16x16x32_bf16 v[16:19], v[158:161], v[232:235], v[16:19]
	v_mfma_f32_16x16x32_bf16 v[20:23], v[188:191], v[204:207], v[20:23]
	v_mfma_f32_16x16x32_bf16 v[24:27], v[188:191], v[232:235], v[24:27]
	v_mfma_f32_16x16x32_bf16 v[28:31], v[196:199], v[204:207], v[28:31]
	v_mfma_f32_16x16x32_bf16 v[32:35], v[196:199], v[232:235], v[32:35]
	v_lshl_add_u32 v5, s14, 13, v7
	s_nop 0
	ds_write2_b32 v5, v36, v8 offset1:16
	ds_write2_b32 v5, v37, v9 offset0:32 offset1:48
	ds_write2_b32 v5, v38, v10 offset0:64 offset1:80
	ds_write2_b32 v5, v39, v11 offset0:96 offset1:112
	v_add_u32_e32 v8, 0x800, v5
	ds_write2_b32 v8, v12, v16 offset1:16
	ds_write2_b32 v8, v13, v17 offset0:32 offset1:48
	ds_write2_b32 v8, v14, v18 offset0:64 offset1:80
	ds_write2_b32 v8, v15, v19 offset0:96 offset1:112
	v_add_u32_e32 v8, 0x1000, v5
	v_add_u32_e32 v5, 0x1800, v5
	ds_write2_b32 v8, v20, v24 offset1:16
	ds_write2_b32 v8, v21, v25 offset0:32 offset1:48
	ds_write2_b32 v8, v22, v26 offset0:64 offset1:80
	ds_write2_b32 v8, v23, v27 offset0:96 offset1:112
	ds_write2_b32 v5, v28, v32 offset1:16
	ds_write2_b32 v5, v29, v33 offset0:32 offset1:48
	ds_write2_b32 v5, v30, v34 offset0:64 offset1:80
	ds_write2_b32 v5, v31, v35 offset0:96 offset1:112
	s_waitcnt lgkmcnt(0)
	s_barrier
	ds_read_b128 v[8:11], v1
	ds_read_b128 v[12:15], v1 offset:8192
	v_add_u32_e32 v36, s7, v6
	v_ashrrev_i32_e32 v37, 31, v36
	v_lshlrev_b64 v[36:37], 11, v[36:37]
	s_waitcnt lgkmcnt(1)
	v_mov_b32_e32 v16, v8
	v_mov_b32_e32 v17, v10
	v_mov_b32_e32 v10, v9
	v_pk_add_f32 v[16:17], v[16:17], 0 op_sel_hi:[1,0]
	s_waitcnt lgkmcnt(0)
	v_mov_b32_e32 v18, v12
	v_mov_b32_e32 v19, v14
	v_pk_add_f32 v[8:9], v[10:11], 0 op_sel_hi:[1,0]
	v_mov_b32_e32 v14, v13
	v_pk_add_f32 v[32:33], v[16:17], v[18:19]
	v_pk_add_f32 v[34:35], v[8:9], v[14:15]
	ds_read_b128 v[8:11], v1 offset:16384
	ds_read_b128 v[12:15], v1 offset:24576
	ds_read_b128 v[16:19], v1 offset:32768
	ds_read_b128 v[20:23], v1 offset:40960
	ds_read_b128 v[24:27], v1 offset:49152
	ds_read_b128 v[28:31], v1 offset:57344
	s_waitcnt lgkmcnt(5)
	v_mov_b32_e32 v38, v8
	v_mov_b32_e32 v39, v10
	v_mov_b32_e32 v10, v9
	v_pk_add_f32 v[32:33], v[32:33], v[38:39]
	v_pk_add_f32 v[8:9], v[34:35], v[10:11]
	s_waitcnt lgkmcnt(4)
	v_mov_b32_e32 v10, v12
	v_mov_b32_e32 v11, v14
	v_pk_add_f32 v[10:11], v[32:33], v[10:11]
	v_mov_b32_e32 v14, v13
	s_waitcnt lgkmcnt(3)
	v_mov_b32_e32 v12, v16
	v_mov_b32_e32 v13, v18
	v_pk_add_f32 v[8:9], v[8:9], v[14:15]
	v_pk_add_f32 v[10:11], v[10:11], v[12:13]
	v_mov_b32_e32 v18, v17
	s_waitcnt lgkmcnt(2)
	v_mov_b32_e32 v12, v20
	v_mov_b32_e32 v13, v22
	v_pk_add_f32 v[8:9], v[8:9], v[18:19]
	v_pk_add_f32 v[10:11], v[10:11], v[12:13]
	v_mov_b32_e32 v22, v21
	s_waitcnt lgkmcnt(1)
	v_mov_b32_e32 v12, v24
	v_mov_b32_e32 v13, v26
	v_pk_add_f32 v[8:9], v[8:9], v[22:23]
	v_pk_add_f32 v[10:11], v[10:11], v[12:13]
	v_mov_b32_e32 v26, v25
	s_waitcnt lgkmcnt(0)
	v_mov_b32_e32 v12, v28
	v_mov_b32_e32 v13, v30
	v_pk_add_f32 v[8:9], v[8:9], v[26:27]
	v_pk_add_f32 v[10:11], v[10:11], v[12:13]
	v_mov_b32_e32 v30, v29
	v_pk_add_f32 v[8:9], v[8:9], v[30:31]
	v_and_b32_sdwa v5, v11, v171 dst_sel:DWORD dst_unused:UNUSED_PAD src0_sel:WORD_1 src1_sel:DWORD
	v_and_b32_sdwa v12, v10, v171 dst_sel:DWORD dst_unused:UNUSED_PAD src0_sel:WORD_1 src1_sel:DWORD
	v_add3_u32 v10, v10, v12, s90
	v_add3_u32 v5, v11, v5, s90
	v_and_b32_sdwa v11, v9, v171 dst_sel:DWORD dst_unused:UNUSED_PAD src0_sel:WORD_1 src1_sel:DWORD
	v_and_b32_sdwa v12, v8, v171 dst_sel:DWORD dst_unused:UNUSED_PAD src0_sel:WORD_1 src1_sel:DWORD
	v_lshl_add_u64 v[36:37], s[12:13], 0, v[36:37]
	s_ashr_i32 s7, s6, 31
	v_add3_u32 v9, v9, v11, s90
	v_add3_u32 v8, v8, v12, s90
	v_lshl_add_u64 v[36:37], s[6:7], 1, v[36:37]
	v_and_b32_e32 v9, 0xffff0000, v9
	v_and_b32_e32 v8, 0xffff0000, v8
	v_lshl_add_u64 v[36:37], v[2:3], 1, v[36:37]
	v_or_b32_sdwa v9, v9, v5 dst_sel:DWORD dst_unused:UNUSED_PAD src0_sel:DWORD src1_sel:WORD_1
	v_or_b32_sdwa v8, v8, v10 dst_sel:DWORD dst_unused:UNUSED_PAD src0_sel:DWORD src1_sel:WORD_1
	global_store_dwordx2 v[36:37], v[8:9], off
	s_barrier
	s_mov_b64 s[6:7], 0
